# v7 + the 40 long MFMA runs of the five GEMM K-loops aligned to 8-byte boundaries (one s_nop in the preceding load segment where needed)
# speedup vs baseline: 1.0126x; 1.0038x over previous
; #define PG8_STAGE(bufoff, gbase, voff) do { _Pragma("unroll") for (int _i = 0; _i < 2; ++_i) \
;         __builtin_amdgcn_global_load_lds((const unsigned*)((const char*)(gbase) + (voff)[_i]), (PG8_LAS unsigned*)(lds + (bufoff) + ldsw + _i * 8192), 16, 0, 0); } while (0)
; #define PG8_LDA(dst, b, h) do { _Pragma("unroll") for (int m = 0; m < 4; ++m) _Pragma("unroll") for (int k = 0; k < 2; ++k) dst[m][k] = *(const PG8_LAS bf16x8*)(lds + PG8_SA(b, h) + aoff + m * 2048 + k * 1024); } while (0)
; #define PG8_LDB(dst, b, h) do { _Pragma("unroll") for (int n = 0; n < 2; ++n) _Pragma("unroll") for (int k = 0; k < 2; ++k) dst[n][k] = *(const PG8_LAS bf16x8*)(lds + PG8_SB(b, h) + boff + n * 2048 + k * 1024); } while (0)
; #define PG8_MMA(ai, bj, At, Bt) do { __builtin_amdgcn_s_setprio(1); _Pragma("unroll") for (int m = 0; m < 4; ++m) _Pragma("unroll") for (int n = 0; n < 2; ++n) _Pragma("unroll") for (int k = 0; k < 2; ++k) \
;         acc[ai][bj][m][n] = __builtin_amdgcn_mfma_f32_16x16x32_bf16(Bt[n][k], At[m][k], acc[ai][bj][m][n], 0, 0, 0); __builtin_amdgcn_s_setprio(0); } while (0)
; #define PG8_WAIT_V(n) asm volatile("s_waitcnt vmcnt(" #n ")" ::: "memory")
; #define PG8_WAIT_L(n) asm volatile("s_waitcnt lgkmcnt(" #n ")" ::: "memory")
; #define PG8_BAR __builtin_amdgcn_s_barrier()
; #define PG8_SCHED __builtin_amdgcn_sched_barrier(0)
; template <class Epi, class Sched, bool ALIGN_EPI = false, bool SP2 = false>
; __device__ __forceinline__ void gemm_phase(PG8_LAS unsigned char* lds, const Gemm g, const Sched& S, const Epi& E) {
;     ...
;             PG8_LDB(B0, 0, 0); PG8_LDB(B1, 0, 1); PG8_SCHED; PG8_LDA(At, 0, 0); PG8_STAGE(PG8_SA(1, 1), a1 + hstep, voffA);
;             PG8_WAIT_V(8); PG8_WAIT_L(0); PG8_BAR; PG8_MMA(0, 0, At, B0); PG8_MMA(0, 1, At, B1); PG8_BAR; PG8_SCHED;
;             PG8_LDA(At, 0, 1); PG8_STAGE(PG8_SB(0, 0), b2, voffB); PG8_STAGE(PG8_SB(0, 1), b2 + hstep, voffB); PG8_STAGE(PG8_SA(0, 0), a2, voffA);
;             PG8_WAIT_V(8); PG8_WAIT_L(0); PG8_BAR; PG8_MMA(1, 0, At, B0); PG8_MMA(1, 1, At, B1); PG8_BAR; PG8_SCHED;
.Lrs_gu_a:
	s_add_i32 s54, 0, 0x14000
	v_add_u32_e32 v156, s52, v141
	v_add_u32_e32 v172, s54, v141
	ds_read_b128 v[144:147], v156
	ds_read_b128 v[148:151], v156 offset:1024
	ds_read_b128 v[152:155], v156 offset:2048
	ds_read_b128 v[156:159], v156 offset:3072
	ds_read_b128 v[160:163], v172
	ds_read_b128 v[164:167], v172 offset:1024
	ds_read_b128 v[168:171], v172 offset:2048
	ds_read_b128 v[172:175], v172 offset:3072
	v_lshl_add_u64 v[214:215], s[0:1], 0, v[136:137]
	s_add_i32 m0, s40, 0xc000
	ds_read_b128 v[176:179], v143
	ds_read_b128 v[180:183], v143 offset:1024
	ds_read_b128 v[194:197], v143 offset:2048
	ds_read_b128 v[198:201], v143 offset:3072
	ds_read_b128 v[202:205], v143 offset:4096
	ds_read_b128 v[206:209], v143 offset:5120
	ds_read_b128 v[210:213], v143 offset:6144
	ds_read_b128 v[228:231], v143 offset:7168
	global_load_lds_dwordx4 v[214:215], off
	v_lshl_add_u64 v[214:215], s[0:1], 0, v[138:139]
	s_add_i32 m0, s40, 0xe000
	s_nop 0
	global_load_lds_dwordx4 v[214:215], off
	s_waitcnt vmcnt(8)
	s_waitcnt lgkmcnt(0)
	s_barrier
	s_setprio 1
	s_waitcnt lgkmcnt(0)
	v_mfma_f32_16x16x32_bf16 v[124:127], v[144:147], v[176:179], v[124:127]
	v_mfma_f32_16x16x32_bf16 v[116:119], v[152:155], v[176:179], v[116:119]
	v_mfma_f32_16x16x32_bf16 v[108:111], v[144:147], v[194:197], v[108:111]
	v_mfma_f32_16x16x32_bf16 v[100:103], v[152:155], v[194:197], v[100:103]
	v_mfma_f32_16x16x32_bf16 v[92:95], v[144:147], v[202:205], v[92:95]
	v_mfma_f32_16x16x32_bf16 v[84:87], v[152:155], v[202:205], v[84:87]
	v_mfma_f32_16x16x32_bf16 v[76:79], v[144:147], v[210:213], v[76:79]
	v_mfma_f32_16x16x32_bf16 v[68:71], v[152:155], v[210:213], v[68:71]
	v_mfma_f32_16x16x32_bf16 v[124:127], v[148:151], v[180:183], v[124:127]
	v_mfma_f32_16x16x32_bf16 v[116:119], v[156:159], v[180:183], v[116:119]
	v_mfma_f32_16x16x32_bf16 v[108:111], v[148:151], v[198:201], v[108:111]
	v_mfma_f32_16x16x32_bf16 v[100:103], v[156:159], v[198:201], v[100:103]
	v_mfma_f32_16x16x32_bf16 v[92:95], v[148:151], v[206:209], v[92:95]
	v_mfma_f32_16x16x32_bf16 v[84:87], v[156:159], v[206:209], v[84:87]
	v_mfma_f32_16x16x32_bf16 v[76:79], v[148:151], v[228:231], v[76:79]
	v_mfma_f32_16x16x32_bf16 v[68:71], v[156:159], v[228:231], v[68:71]
	s_setprio 0
	s_setprio 1
	v_mfma_f32_16x16x32_bf16 v[120:123], v[160:163], v[176:179], v[120:123]
	v_mfma_f32_16x16x32_bf16 v[112:115], v[168:171], v[176:179], v[112:115]
	v_mfma_f32_16x16x32_bf16 v[104:107], v[160:163], v[194:197], v[104:107]
	v_mfma_f32_16x16x32_bf16 v[96:99], v[168:171], v[194:197], v[96:99]
	v_mfma_f32_16x16x32_bf16 v[88:91], v[160:163], v[202:205], v[88:91]
	v_mfma_f32_16x16x32_bf16 v[80:83], v[168:171], v[202:205], v[80:83]
	v_mfma_f32_16x16x32_bf16 v[72:75], v[160:163], v[210:213], v[72:75]
	v_mfma_f32_16x16x32_bf16 v[64:67], v[168:171], v[210:213], v[64:67]
	v_mfma_f32_16x16x32_bf16 v[120:123], v[164:167], v[180:183], v[120:123]
	v_mfma_f32_16x16x32_bf16 v[112:115], v[172:175], v[180:183], v[112:115]
	v_mfma_f32_16x16x32_bf16 v[104:107], v[164:167], v[198:201], v[104:107]
	v_mfma_f32_16x16x32_bf16 v[96:99], v[172:175], v[198:201], v[96:99]
	v_mfma_f32_16x16x32_bf16 v[88:91], v[164:167], v[206:209], v[88:91]
	v_mfma_f32_16x16x32_bf16 v[80:83], v[172:175], v[206:209], v[80:83]
	v_mfma_f32_16x16x32_bf16 v[72:75], v[164:167], v[228:231], v[72:75]
	v_mfma_f32_16x16x32_bf16 v[64:67], v[172:175], v[228:231], v[64:67]
	s_setprio 0
	s_barrier
	s_add_i32 s52, s52, s39
	v_lshl_add_u64 v[214:215], s[24:25], 0, v[132:133]
	s_mov_b32 m0, s52
	ds_read_b128 v[176:179], v143 offset:16384
	ds_read_b128 v[180:183], v143 offset:17408
	ds_read_b128 v[194:197], v143 offset:18432
	ds_read_b128 v[198:201], v143 offset:19456
	ds_read_b128 v[202:205], v143 offset:20480
	ds_read_b128 v[206:209], v143 offset:21504
	ds_read_b128 v[210:213], v143 offset:22528
	ds_read_b128 v[228:231], v143 offset:23552
	global_load_lds_dwordx4 v[214:215], off
	s_add_i32 m0, s52, 0x2000
	s_add_u32 s52, s24, 0x40000
	v_lshl_add_u64 v[224:225], s[24:25], 0, v[128:129]
	s_addc_u32 s53, s25, 0
	s_add_i32 s54, s54, s39
	global_load_lds_dwordx4 v[224:225], off
	v_lshl_add_u64 v[226:227], s[52:53], 0, v[132:133]
	s_mov_b32 m0, s54
	v_lshl_add_u64 v[232:233], s[26:27], 0, v[130:131]
	global_load_lds_dwordx4 v[226:227], off
	v_lshl_add_u64 v[226:227], s[52:53], 0, v[128:129]
	s_add_i32 m0, s54, 0x2000
	s_nop 0
	global_load_lds_dwordx4 v[226:227], off
	v_lshl_add_u64 v[226:227], s[26:27], 0, v[134:135]
	s_mov_b32 m0, s40
	s_nop 0
	global_load_lds_dwordx4 v[226:227], off
	s_mov_b32 m0, s41
	s_nop 0
	global_load_lds_dwordx4 v[232:233], off
	s_nop 0
	s_waitcnt vmcnt(8)
	s_waitcnt lgkmcnt(0)
	s_barrier
; __device__ __forceinline__ float sum4(const f32x4 a) { return (a[0] + a[1]) + (a[2] + a[3]); }
; #define PG8_STAGE(bufoff, gbase, voff) do { _Pragma("unroll") for (int _i = 0; _i < 2; ++_i) \
;         __builtin_amdgcn_global_load_lds((const unsigned*)((const char*)(gbase) + (voff)[_i]), (PG8_LAS unsigned*)(lds + (bufoff) + ldsw + _i * 8192), 16, 0, 0); } while (0)
; #define PG8_LDA(dst, b, h) do { _Pragma("unroll") for (int m = 0; m < 4; ++m) _Pragma("unroll") for (int k = 0; k < 2; ++k) dst[m][k] = *(const PG8_LAS bf16x8*)(lds + PG8_SA(b, h) + aoff + m * 2048 + k * 1024); } while (0)
; #define PG8_LDB(dst, b, h) do { _Pragma("unroll") for (int n = 0; n < 2; ++n) _Pragma("unroll") for (int k = 0; k < 2; ++k) dst[n][k] = *(const PG8_LAS bf16x8*)(lds + PG8_SB(b, h) + boff + n * 2048 + k * 1024); } while (0)
; #define PG8_MMA(ai, bj, At, Bt) do { __builtin_amdgcn_s_setprio(1); _Pragma("unroll") for (int m = 0; m < 4; ++m) _Pragma("unroll") for (int n = 0; n < 2; ++n) _Pragma("unroll") for (int k = 0; k < 2; ++k) \
;         acc[ai][bj][m][n] = __builtin_amdgcn_mfma_f32_16x16x32_bf16(Bt[n][k], At[m][k], acc[ai][bj][m][n], 0, 0, 0); __builtin_amdgcn_s_setprio(0); } while (0)
; #define PG8_WAIT_V(n) asm volatile("s_waitcnt vmcnt(" #n ")" ::: "memory")
; __device__ __forceinline__ float row_rstd(const float* ps_row) {
;     const f32x4* p = (const f32x4*)ps_row; const f32x4 a = p[0], b = p[1], c = p[2], d = p[3];
;     const float s = (sum4(a) + sum4(b)) + (sum4(c) + sum4(d));
;     return 1.0f / sqrtf(s * (1.0f / 1024.0f) + E_EPS);
; }
; template <class Epi, class Sched, bool ALIGN_EPI = false, bool SP2 = false>
; __device__ __forceinline__ void gemm_phase(PG8_LAS unsigned char* lds, const Gemm g, const Sched& S, const Epi& E) {
;     ...
;             PG8_WAIT_V(8); PG8_WAIT_L(0); PG8_BAR; PG8_MMA(0, 0, At, B0); PG8_MMA(0, 1, At, B1); PG8_BAR; PG8_SCHED;
;             PG8_LDA(At, 0, 1); PG8_STAGE(PG8_SB(0, 0), b2, voffB); PG8_STAGE(PG8_SB(0, 1), b2 + hstep, voffB); PG8_STAGE(PG8_SA(0, 0), a2, voffA);
;             PG8_WAIT_V(8); PG8_WAIT_L(0); PG8_BAR; PG8_MMA(1, 0, At, B0); PG8_MMA(1, 1, At, B1); PG8_BAR; PG8_SCHED;
;             PG8_LDB(B0, 1, 0); PG8_LDB(B1, 1, 1); PG8_SCHED; PG8_LDA(At, 1, 0); PG8_STAGE(PG8_SA(0, 1), a2 + hstep, voffA);
;             PG8_WAIT_V(8); PG8_WAIT_L(0); PG8_BAR; PG8_MMA(0, 0, At, B0); PG8_MMA(0, 1, At, B1); PG8_BAR; PG8_SCHED;
	s_setprio 1
	s_waitcnt lgkmcnt(0)
	v_mfma_f32_16x16x32_bf16 v[60:63], v[144:147], v[176:179], v[60:63]
	v_mfma_f32_16x16x32_bf16 v[52:55], v[152:155], v[176:179], v[52:55]
	v_mfma_f32_16x16x32_bf16 v[44:47], v[144:147], v[194:197], v[44:47]
	v_mfma_f32_16x16x32_bf16 v[36:39], v[152:155], v[194:197], v[36:39]
	v_mfma_f32_16x16x32_bf16 v[28:31], v[144:147], v[202:205], v[28:31]
	v_mfma_f32_16x16x32_bf16 v[20:23], v[152:155], v[202:205], v[20:23]
	v_mfma_f32_16x16x32_bf16 v[12:15], v[144:147], v[210:213], v[12:15]
	v_mfma_f32_16x16x32_bf16 v[4:7], v[152:155], v[210:213], v[4:7]
	v_mfma_f32_16x16x32_bf16 v[60:63], v[148:151], v[180:183], v[60:63]
	v_mfma_f32_16x16x32_bf16 v[52:55], v[156:159], v[180:183], v[52:55]
	v_mfma_f32_16x16x32_bf16 v[44:47], v[148:151], v[198:201], v[44:47]
	v_mfma_f32_16x16x32_bf16 v[36:39], v[156:159], v[198:201], v[36:39]
	v_mfma_f32_16x16x32_bf16 v[28:31], v[148:151], v[206:209], v[28:31]
	v_mfma_f32_16x16x32_bf16 v[20:23], v[156:159], v[206:209], v[20:23]
	v_mfma_f32_16x16x32_bf16 v[12:15], v[148:151], v[228:231], v[12:15]
	v_mfma_f32_16x16x32_bf16 v[4:7], v[156:159], v[228:231], v[4:7]
	s_setprio 0
	s_setprio 1
	v_mfma_f32_16x16x32_bf16 v[56:59], v[160:163], v[176:179], v[56:59]
	v_mfma_f32_16x16x32_bf16 v[48:51], v[168:171], v[176:179], v[48:51]
	v_mfma_f32_16x16x32_bf16 v[40:43], v[160:163], v[194:197], v[40:43]
	v_mfma_f32_16x16x32_bf16 v[32:35], v[168:171], v[194:197], v[32:35]
	v_mfma_f32_16x16x32_bf16 v[24:27], v[160:163], v[202:205], v[24:27]
	v_mfma_f32_16x16x32_bf16 v[16:19], v[168:171], v[202:205], v[16:19]
	v_mfma_f32_16x16x32_bf16 v[8:11], v[160:163], v[210:213], v[8:11]
	v_mfma_f32_16x16x32_bf16 v[0:3], v[168:171], v[210:213], v[0:3]
	v_mfma_f32_16x16x32_bf16 v[56:59], v[164:167], v[180:183], v[56:59]
	v_mfma_f32_16x16x32_bf16 v[48:51], v[172:175], v[180:183], v[48:51]
	v_mfma_f32_16x16x32_bf16 v[40:43], v[164:167], v[198:201], v[40:43]
	v_mfma_f32_16x16x32_bf16 v[32:35], v[172:175], v[198:201], v[32:35]
	v_mfma_f32_16x16x32_bf16 v[24:27], v[164:167], v[206:209], v[24:27]
	v_mfma_f32_16x16x32_bf16 v[16:19], v[172:175], v[206:209], v[16:19]
	v_mfma_f32_16x16x32_bf16 v[8:11], v[164:167], v[228:231], v[8:11]
	v_mfma_f32_16x16x32_bf16 v[0:3], v[172:175], v[228:231], v[0:3]
	s_setprio 0
	s_barrier
	s_add_i32 s52, 0, 0x18000
	s_add_i32 s53, 0, 0x1c000
	s_cmp_eq_u32 s51, 12
	s_cbranch_scc0 .Lrs_gu_b
	s_cmp_lt_u32 s39, 0x1000
	s_cbranch_scc0 .Lrs_gu_b
	v_add_f32_e32 v236, v236, v237
	v_add_f32_e32 v238, v238, v239
	v_add_f32_e32 v240, v240, v241
	v_add_f32_e32 v242, v242, v243
	v_add_f32_e32 v244, v244, v245
	v_add_f32_e32 v246, v246, v247
	v_add_f32_e32 v248, v248, v249
	v_add_f32_e32 v190, v190, v191
	v_add_f32_e32 v236, v236, v238
	v_add_f32_e32 v240, v240, v242
	v_add_f32_e32 v244, v244, v246
	v_add_f32_e32 v248, v248, v190
	v_add_f32_e32 v236, v236, v240
	v_add_f32_e32 v244, v244, v248
	v_add_f32_e32 v237, v236, v244
	s_mov_b32 s98, 0xf800000
	v_fmamk_f32 v237, v237, 0x3a800000, v218
	v_mul_f32_e32 v238, 0x4f800000, v237
	v_cmp_gt_f32_e32 vcc, s98, v237
	s_nop 1
	v_cndmask_b32_e32 v237, v237, v238, vcc
	v_sqrt_f32_e32 v238, v237
	s_nop 0
	v_add_u32_e32 v239, -1, v238
	v_add_u32_e32 v240, 1, v238
	v_fma_f32 v241, -v239, v238, v237
	v_fma_f32 v242, -v240, v238, v237
	v_cmp_ge_f32_e64 s[98:99], 0, v241
	s_nop 1
	v_cndmask_b32_e64 v238, v238, v239, s[98:99]
	v_cmp_lt_f32_e64 s[98:99], 0, v242
	s_nop 1
	v_cndmask_b32_e64 v238, v238, v240, s[98:99]
	v_mul_f32_e32 v239, 0x37800000, v238
	v_cndmask_b32_e32 v238, v238, v239, vcc
	v_cmp_class_f32_e32 vcc, v237, v219
	s_nop 1
	v_cndmask_b32_e32 v237, v238, v237, vcc
	v_div_scale_f32 v238, s[98:99], v237, v237, 1.0
	v_rcp_f32_e32 v239, v238
	v_div_scale_f32 v240, vcc, 1.0, v237, 1.0
	v_fma_f32 v241, -v238, v239, 1.0
	v_fmac_f32_e32 v239, v241, v239
	v_mul_f32_e32 v241, v240, v239
	v_fma_f32 v242, -v238, v241, v240
	v_fmac_f32_e32 v241, v242, v239
	v_fma_f32 v238, -v238, v241, v240
	v_div_fmas_f32 v238, v238, v239, v241
	v_div_fixup_f32 v237, v238, v237, 1.0
	v_lshl_add_u32 v250, v216, 2, 0
	v_add_u32_e32 v250, 0x20000, v250
	ds_write_b32 v250, v237

; #define PG8_STAGE(bufoff, gbase, voff) do { _Pragma("unroll") for (int _i = 0; _i < 2; ++_i) \
;         __builtin_amdgcn_global_load_lds((const unsigned*)((const char*)(gbase) + (voff)[_i]), (PG8_LAS unsigned*)(lds + (bufoff) + ldsw + _i * 8192), 16, 0, 0); } while (0)
; #define PG8_LDA(dst, b, h) do { _Pragma("unroll") for (int m = 0; m < 4; ++m) _Pragma("unroll") for (int k = 0; k < 2; ++k) dst[m][k] = *(const PG8_LAS bf16x8*)(lds + PG8_SA(b, h) + aoff + m * 2048 + k * 1024); } while (0)
; #define PG8_LDB(dst, b, h) do { _Pragma("unroll") for (int n = 0; n < 2; ++n) _Pragma("unroll") for (int k = 0; k < 2; ++k) dst[n][k] = *(const PG8_LAS bf16x8*)(lds + PG8_SB(b, h) + boff + n * 2048 + k * 1024); } while (0)
; #define PG8_MMA(ai, bj, At, Bt) do { __builtin_amdgcn_s_setprio(1); _Pragma("unroll") for (int m = 0; m < 4; ++m) _Pragma("unroll") for (int n = 0; n < 2; ++n) _Pragma("unroll") for (int k = 0; k < 2; ++k) \
;         acc[ai][bj][m][n] = __builtin_amdgcn_mfma_f32_16x16x32_bf16(Bt[n][k], At[m][k], acc[ai][bj][m][n], 0, 0, 0); __builtin_amdgcn_s_setprio(0); } while (0)
; #define PG8_WAIT_V(n) asm volatile("s_waitcnt vmcnt(" #n ")" ::: "memory")
; #define PG8_WAIT_L(n) asm volatile("s_waitcnt lgkmcnt(" #n ")" ::: "memory")
; #define PG8_BAR __builtin_amdgcn_s_barrier()
; #define PG8_SCHED __builtin_amdgcn_sched_barrier(0)
; template <class Epi, class Sched, bool ALIGN_EPI = false, bool SP2 = false>
; __device__ __forceinline__ void gemm_phase(PG8_LAS unsigned char* lds, const Gemm g, const Sched& S, const Epi& E) {
;     ...
;             PG8_LDB(B0, 0, 0); PG8_LDB(B1, 0, 1); PG8_SCHED; PG8_LDA(At, 0, 0); PG8_STAGE(PG8_SA(1, 1), a1 + hstep, voffA);
;             PG8_WAIT_V(8); PG8_WAIT_L(0); PG8_BAR; PG8_MMA(0, 0, At, B0); PG8_MMA(0, 1, At, B1); PG8_BAR; PG8_SCHED;
;             PG8_LDA(At, 0, 1); PG8_STAGE(PG8_SB(0, 0), b2, voffB); PG8_STAGE(PG8_SB(0, 1), b2 + hstep, voffB); PG8_STAGE(PG8_SA(0, 0), a2, voffA);
;             PG8_WAIT_V(8); PG8_WAIT_L(0); PG8_BAR; PG8_MMA(1, 0, At, B0); PG8_MMA(1, 1, At, B1); PG8_BAR; PG8_SCHED;
.LBB0_218:
	s_add_u32 s25, s0, 0xfffc0080
	s_addc_u32 s40, s1, -1
	s_cmp_eq_u32 s93, 12
	s_cselect_b32 s43, s4, s40
	s_cselect_b32 s42, s5, s25
	s_cselect_b32 s41, s27, s92
	s_cselect_b32 s40, s58, s59
	s_add_i32 s94, 0, 0x10000
	s_add_i32 s25, 0, 0x14000
	v_add_u32_e32 v140, s94, v228
	v_add_u32_e32 v156, s25, v228
	ds_read_b128 v[128:131], v140
	ds_read_b128 v[132:135], v140 offset:1024
	ds_read_b128 v[136:139], v140 offset:2048
	ds_read_b128 v[140:143], v140 offset:3072
	ds_read_b128 v[144:147], v156
	ds_read_b128 v[148:151], v156 offset:1024
	ds_read_b128 v[152:155], v156 offset:2048
	ds_read_b128 v[156:159], v156 offset:3072
	s_add_i32 m0, s45, 0xc000
	ds_read_b128 v[160:163], v230
	ds_read_b128 v[164:167], v230 offset:1024
	ds_read_b128 v[168:171], v230 offset:2048
	ds_read_b128 v[172:175], v230 offset:3072
	ds_read_b128 v[176:179], v230 offset:4096
	ds_read_b128 v[180:183], v230 offset:5120
	ds_read_b128 v[204:207], v230 offset:6144
	ds_read_b128 v[208:211], v230 offset:7168
	ds_read_b128 v[212:215], v249
	ds_read_b128 v[232:235], v249 offset:1024
	global_load_lds_dwordx4 v198, s[0:1]
	s_add_i32 m0, s45, 0xe000
	s_nop 0
	global_load_lds_dwordx4 v196, s[0:1]
	s_waitcnt vmcnt(9)
	s_waitcnt lgkmcnt(0)
	s_barrier
	s_setprio 1
	s_waitcnt lgkmcnt(0)
	v_mfma_f32_16x16x32_bf16 v[124:127], v[128:131], v[160:163], v[124:127]
	v_mfma_f32_16x16x32_bf16 v[120:123], v[136:139], v[160:163], v[120:123]
	v_mfma_f32_16x16x32_bf16 v[108:111], v[128:131], v[168:171], v[108:111]
	v_mfma_f32_16x16x32_bf16 v[104:107], v[136:139], v[168:171], v[104:107]
	v_mfma_f32_16x16x32_bf16 v[92:95], v[128:131], v[176:179], v[92:95]
	v_mfma_f32_16x16x32_bf16 v[88:91], v[136:139], v[176:179], v[88:91]
	v_mfma_f32_16x16x32_bf16 v[76:79], v[128:131], v[204:207], v[76:79]
	v_mfma_f32_16x16x32_bf16 v[72:75], v[136:139], v[204:207], v[72:75]
	v_mfma_f32_16x16x32_bf16 v[124:127], v[132:135], v[164:167], v[124:127]
	v_mfma_f32_16x16x32_bf16 v[120:123], v[140:143], v[164:167], v[120:123]
	v_mfma_f32_16x16x32_bf16 v[108:111], v[132:135], v[172:175], v[108:111]
	v_mfma_f32_16x16x32_bf16 v[104:107], v[140:143], v[172:175], v[104:107]
	v_mfma_f32_16x16x32_bf16 v[92:95], v[132:135], v[180:183], v[92:95]
	v_mfma_f32_16x16x32_bf16 v[88:91], v[140:143], v[180:183], v[88:91]
	v_mfma_f32_16x16x32_bf16 v[76:79], v[132:135], v[208:211], v[76:79]
	v_mfma_f32_16x16x32_bf16 v[72:75], v[140:143], v[208:211], v[72:75]
	s_setprio 0
	s_setprio 1
	v_mfma_f32_16x16x32_bf16 v[116:119], v[144:147], v[160:163], v[116:119]
	v_mfma_f32_16x16x32_bf16 v[112:115], v[152:155], v[160:163], v[112:115]
	v_mfma_f32_16x16x32_bf16 v[100:103], v[144:147], v[168:171], v[100:103]
	v_mfma_f32_16x16x32_bf16 v[96:99], v[152:155], v[168:171], v[96:99]
	v_mfma_f32_16x16x32_bf16 v[84:87], v[144:147], v[176:179], v[84:87]
	v_mfma_f32_16x16x32_bf16 v[80:83], v[152:155], v[176:179], v[80:83]
	v_mfma_f32_16x16x32_bf16 v[68:71], v[144:147], v[204:207], v[68:71]
	v_mfma_f32_16x16x32_bf16 v[64:67], v[152:155], v[204:207], v[64:67]
	v_mfma_f32_16x16x32_bf16 v[116:119], v[148:151], v[164:167], v[116:119]
	v_mfma_f32_16x16x32_bf16 v[112:115], v[156:159], v[164:167], v[112:115]
	v_mfma_f32_16x16x32_bf16 v[100:103], v[148:151], v[172:175], v[100:103]
	v_mfma_f32_16x16x32_bf16 v[96:99], v[156:159], v[172:175], v[96:99]
	v_mfma_f32_16x16x32_bf16 v[84:87], v[148:151], v[180:183], v[84:87]
	v_mfma_f32_16x16x32_bf16 v[80:83], v[156:159], v[180:183], v[80:83]
	v_mfma_f32_16x16x32_bf16 v[68:71], v[148:151], v[208:211], v[68:71]
	v_mfma_f32_16x16x32_bf16 v[64:67], v[156:159], v[208:211], v[64:67]
	v_mfma_f32_16x16x32_bf16 v[236:239], v[128:131], v[212:215], v[236:239]
	v_mfma_f32_16x16x32_bf16 v[240:243], v[136:139], v[212:215], v[240:243]
	v_mfma_f32_16x16x32_bf16 v[244:247], v[144:147], v[212:215], v[244:247]
	v_mfma_f32_16x16x32_bf16 v[200:203], v[152:155], v[212:215], v[200:203]
	v_mfma_f32_16x16x32_bf16 v[236:239], v[132:135], v[232:235], v[236:239]
	v_mfma_f32_16x16x32_bf16 v[240:243], v[140:143], v[232:235], v[240:243]
	v_mfma_f32_16x16x32_bf16 v[244:247], v[148:151], v[232:235], v[244:247]
	v_mfma_f32_16x16x32_bf16 v[200:203], v[156:159], v[232:235], v[200:203]
	s_setprio 0
	s_barrier
	s_add_i32 s94, s94, s44
	s_mov_b32 m0, s94
	ds_read_b128 v[160:163], v230 offset:16384
	ds_read_b128 v[164:167], v230 offset:17408
	ds_read_b128 v[168:171], v230 offset:18432
	ds_read_b128 v[172:175], v230 offset:19456
	ds_read_b128 v[176:179], v230 offset:20480
	ds_read_b128 v[180:183], v230 offset:21504
	ds_read_b128 v[204:207], v230 offset:22528
	ds_read_b128 v[208:211], v230 offset:23552
	global_load_lds_dwordx4 v184, s[40:41]
	s_add_i32 m0, s94, 0x2000
	s_add_u32 s98, s40, 0x40000
	s_addc_u32 s99, s41, 0
	s_add_i32 s25, s25, s44
	global_load_lds_dwordx4 v194, s[40:41]
	s_mov_b32 m0, s25
	s_nop 0
	global_load_lds_dwordx4 v184, s[98:99]
	s_add_i32 m0, s25, 0x2000
	s_nop 0
	global_load_lds_dwordx4 v194, s[98:99]
	s_mov_b32 m0, s45
	s_nop 0
	global_load_lds_dwordx4 v198, s[42:43]
	s_mov_b32 m0, s46
	s_nop 0
	global_load_lds_dwordx4 v196, s[42:43]
	s_and_b32 m0, s44, 0xc00
	s_add_i32 m0, m0, 0x20800
	s_nop 0
	global_load_lds_dwordx4 v248, s[42:43]
	s_nop 0
	s_waitcnt vmcnt(9)
	s_waitcnt lgkmcnt(0)
	s_barrier
; #define PG8_STAGE(bufoff, gbase, voff) do { _Pragma("unroll") for (int _i = 0; _i < 2; ++_i) \
;         __builtin_amdgcn_global_load_lds((const unsigned*)((const char*)(gbase) + (voff)[_i]), (PG8_LAS unsigned*)(lds + (bufoff) + ldsw + _i * 8192), 16, 0, 0); } while (0)
; #define PG8_LDA(dst, b, h) do { _Pragma("unroll") for (int m = 0; m < 4; ++m) _Pragma("unroll") for (int k = 0; k < 2; ++k) dst[m][k] = *(const PG8_LAS bf16x8*)(lds + PG8_SA(b, h) + aoff + m * 2048 + k * 1024); } while (0)
; #define PG8_LDB(dst, b, h) do { _Pragma("unroll") for (int n = 0; n < 2; ++n) _Pragma("unroll") for (int k = 0; k < 2; ++k) dst[n][k] = *(const PG8_LAS bf16x8*)(lds + PG8_SB(b, h) + boff + n * 2048 + k * 1024); } while (0)
; #define PG8_MMA(ai, bj, At, Bt) do { __builtin_amdgcn_s_setprio(1); _Pragma("unroll") for (int m = 0; m < 4; ++m) _Pragma("unroll") for (int n = 0; n < 2; ++n) _Pragma("unroll") for (int k = 0; k < 2; ++k) \
;         acc[ai][bj][m][n] = __builtin_amdgcn_mfma_f32_16x16x32_bf16(Bt[n][k], At[m][k], acc[ai][bj][m][n], 0, 0, 0); __builtin_amdgcn_s_setprio(0); } while (0)
; #define PG8_WAIT_V(n) asm volatile("s_waitcnt vmcnt(" #n ")" ::: "memory")
; #define PG8_WAIT_L(n) asm volatile("s_waitcnt lgkmcnt(" #n ")" ::: "memory")
; #define PG8_BAR __builtin_amdgcn_s_barrier()
; #define PG8_SCHED __builtin_amdgcn_sched_barrier(0)
; template <class Epi, class Sched, bool ALIGN_EPI = false, bool SP2 = false>
; __device__ __forceinline__ void gemm_phase(PG8_LAS unsigned char* lds, const Gemm g, const Sched& S, const Epi& E) {
;     ...
;             PG8_WAIT_V(8); PG8_WAIT_L(0); PG8_BAR; PG8_MMA(1, 0, At, B0); PG8_MMA(1, 1, At, B1); PG8_BAR; PG8_SCHED;
;             PG8_LDB(B0, 1, 0); PG8_LDB(B1, 1, 1); PG8_SCHED; PG8_LDA(At, 1, 0); PG8_STAGE(PG8_SA(0, 1), a2 + hstep, voffA);
;             PG8_WAIT_V(8); PG8_WAIT_L(0); PG8_BAR; PG8_MMA(0, 0, At, B0); PG8_MMA(0, 1, At, B1); PG8_BAR; PG8_SCHED;
	s_setprio 1
	s_waitcnt lgkmcnt(0)
	v_mfma_f32_16x16x32_bf16 v[60:63], v[128:131], v[160:163], v[60:63]
	v_mfma_f32_16x16x32_bf16 v[56:59], v[136:139], v[160:163], v[56:59]
	v_mfma_f32_16x16x32_bf16 v[44:47], v[128:131], v[168:171], v[44:47]
	v_mfma_f32_16x16x32_bf16 v[40:43], v[136:139], v[168:171], v[40:43]
	v_mfma_f32_16x16x32_bf16 v[28:31], v[128:131], v[176:179], v[28:31]
	v_mfma_f32_16x16x32_bf16 v[24:27], v[136:139], v[176:179], v[24:27]
	v_mfma_f32_16x16x32_bf16 v[12:15], v[128:131], v[204:207], v[12:15]
	v_mfma_f32_16x16x32_bf16 v[8:11], v[136:139], v[204:207], v[8:11]
	v_mfma_f32_16x16x32_bf16 v[60:63], v[132:135], v[164:167], v[60:63]
	v_mfma_f32_16x16x32_bf16 v[56:59], v[140:143], v[164:167], v[56:59]
	v_mfma_f32_16x16x32_bf16 v[44:47], v[132:135], v[172:175], v[44:47]
	v_mfma_f32_16x16x32_bf16 v[40:43], v[140:143], v[172:175], v[40:43]
	v_mfma_f32_16x16x32_bf16 v[28:31], v[132:135], v[180:183], v[28:31]
	v_mfma_f32_16x16x32_bf16 v[24:27], v[140:143], v[180:183], v[24:27]
	v_mfma_f32_16x16x32_bf16 v[12:15], v[132:135], v[208:211], v[12:15]
	v_mfma_f32_16x16x32_bf16 v[8:11], v[140:143], v[208:211], v[8:11]
	s_setprio 0
	s_setprio 1
	v_mfma_f32_16x16x32_bf16 v[52:55], v[144:147], v[160:163], v[52:55]
	v_mfma_f32_16x16x32_bf16 v[48:51], v[152:155], v[160:163], v[48:51]
	v_mfma_f32_16x16x32_bf16 v[36:39], v[144:147], v[168:171], v[36:39]
	v_mfma_f32_16x16x32_bf16 v[32:35], v[152:155], v[168:171], v[32:35]
	v_mfma_f32_16x16x32_bf16 v[20:23], v[144:147], v[176:179], v[20:23]
	v_mfma_f32_16x16x32_bf16 v[16:19], v[152:155], v[176:179], v[16:19]
	v_mfma_f32_16x16x32_bf16 v[4:7], v[144:147], v[204:207], v[4:7]
	v_mfma_f32_16x16x32_bf16 v[0:3], v[152:155], v[204:207], v[0:3]
	v_mfma_f32_16x16x32_bf16 v[52:55], v[148:151], v[164:167], v[52:55]
	v_mfma_f32_16x16x32_bf16 v[48:51], v[156:159], v[164:167], v[48:51]
	v_mfma_f32_16x16x32_bf16 v[36:39], v[148:151], v[172:175], v[36:39]
	v_mfma_f32_16x16x32_bf16 v[32:35], v[156:159], v[172:175], v[32:35]
	v_mfma_f32_16x16x32_bf16 v[20:23], v[148:151], v[180:183], v[20:23]
	v_mfma_f32_16x16x32_bf16 v[16:19], v[156:159], v[180:183], v[16:19]
	v_mfma_f32_16x16x32_bf16 v[4:7], v[148:151], v[208:211], v[4:7]
	v_mfma_f32_16x16x32_bf16 v[0:3], v[156:159], v[208:211], v[0:3]
	s_setprio 0
	s_barrier
	s_add_i32 s25, 0, 0x18000
	s_add_i32 s94, 0, 0x1c000
	v_add_u32_e32 v140, s25, v228
	v_add_u32_e32 v156, s94, v228
	ds_read_b128 v[128:131], v140
	ds_read_b128 v[132:135], v140 offset:1024
	ds_read_b128 v[136:139], v140 offset:2048
	ds_read_b128 v[140:143], v140 offset:3072
	ds_read_b128 v[144:147], v156
	ds_read_b128 v[148:151], v156 offset:1024
	ds_read_b128 v[152:155], v156 offset:2048
	ds_read_b128 v[156:159], v156 offset:3072
	s_add_u32 s98, s42, 0x40000
	s_addc_u32 s99, s43, 0
	s_mov_b32 m0, s47
	ds_read_b128 v[160:163], v230 offset:32768
	ds_read_b128 v[164:167], v230 offset:33792
	ds_read_b128 v[168:171], v230 offset:34816
	ds_read_b128 v[172:175], v230 offset:35840
	ds_read_b128 v[176:179], v230 offset:36864
	ds_read_b128 v[180:183], v230 offset:37888
	ds_read_b128 v[204:207], v230 offset:38912
	ds_read_b128 v[208:211], v230 offset:39936
	ds_read_b128 v[212:215], v249 offset:4096
	ds_read_b128 v[232:235], v249 offset:5120
	global_load_lds_dwordx4 v198, s[98:99]
	s_mov_b32 m0, s48
	s_nop 0
	global_load_lds_dwordx4 v196, s[98:99]
	s_nop 0
	s_waitcnt vmcnt(9)
	s_waitcnt lgkmcnt(0)
	s_barrier
	s_setprio 1
	s_waitcnt lgkmcnt(0)
	v_mfma_f32_16x16x32_bf16 v[124:127], v[128:131], v[160:163], v[124:127]
	v_mfma_f32_16x16x32_bf16 v[120:123], v[136:139], v[160:163], v[120:123]
	v_mfma_f32_16x16x32_bf16 v[108:111], v[128:131], v[168:171], v[108:111]
	v_mfma_f32_16x16x32_bf16 v[104:107], v[136:139], v[168:171], v[104:107]
	v_mfma_f32_16x16x32_bf16 v[92:95], v[128:131], v[176:179], v[92:95]
	v_mfma_f32_16x16x32_bf16 v[88:91], v[136:139], v[176:179], v[88:91]
	v_mfma_f32_16x16x32_bf16 v[76:79], v[128:131], v[204:207], v[76:79]
	v_mfma_f32_16x16x32_bf16 v[72:75], v[136:139], v[204:207], v[72:75]
	v_mfma_f32_16x16x32_bf16 v[124:127], v[132:135], v[164:167], v[124:127]
	v_mfma_f32_16x16x32_bf16 v[120:123], v[140:143], v[164:167], v[120:123]
	v_mfma_f32_16x16x32_bf16 v[108:111], v[132:135], v[172:175], v[108:111]
	v_mfma_f32_16x16x32_bf16 v[104:107], v[140:143], v[172:175], v[104:107]
	v_mfma_f32_16x16x32_bf16 v[92:95], v[132:135], v[180:183], v[92:95]
	v_mfma_f32_16x16x32_bf16 v[88:91], v[140:143], v[180:183], v[88:91]
	v_mfma_f32_16x16x32_bf16 v[76:79], v[132:135], v[208:211], v[76:79]
	v_mfma_f32_16x16x32_bf16 v[72:75], v[140:143], v[208:211], v[72:75]
	s_setprio 0
	s_setprio 1
	v_mfma_f32_16x16x32_bf16 v[116:119], v[144:147], v[160:163], v[116:119]
	v_mfma_f32_16x16x32_bf16 v[112:115], v[152:155], v[160:163], v[112:115]
	v_mfma_f32_16x16x32_bf16 v[100:103], v[144:147], v[168:171], v[100:103]
	v_mfma_f32_16x16x32_bf16 v[96:99], v[152:155], v[168:171], v[96:99]
	v_mfma_f32_16x16x32_bf16 v[84:87], v[144:147], v[176:179], v[84:87]
	v_mfma_f32_16x16x32_bf16 v[80:83], v[152:155], v[176:179], v[80:83]
	v_mfma_f32_16x16x32_bf16 v[68:71], v[144:147], v[204:207], v[68:71]
	v_mfma_f32_16x16x32_bf16 v[64:67], v[152:155], v[204:207], v[64:67]
	v_mfma_f32_16x16x32_bf16 v[116:119], v[148:151], v[164:167], v[116:119]
	v_mfma_f32_16x16x32_bf16 v[112:115], v[156:159], v[164:167], v[112:115]
	v_mfma_f32_16x16x32_bf16 v[100:103], v[148:151], v[172:175], v[100:103]
	v_mfma_f32_16x16x32_bf16 v[96:99], v[156:159], v[172:175], v[96:99]
	v_mfma_f32_16x16x32_bf16 v[84:87], v[148:151], v[180:183], v[84:87]
	v_mfma_f32_16x16x32_bf16 v[80:83], v[156:159], v[180:183], v[80:83]
	v_mfma_f32_16x16x32_bf16 v[68:71], v[148:151], v[208:211], v[68:71]
	v_mfma_f32_16x16x32_bf16 v[64:67], v[156:159], v[208:211], v[64:67]
	v_mfma_f32_16x16x32_bf16 v[236:239], v[128:131], v[212:215], v[236:239]
	v_mfma_f32_16x16x32_bf16 v[240:243], v[136:139], v[212:215], v[240:243]
	v_mfma_f32_16x16x32_bf16 v[244:247], v[144:147], v[212:215], v[244:247]
	v_mfma_f32_16x16x32_bf16 v[200:203], v[152:155], v[212:215], v[200:203]
	v_mfma_f32_16x16x32_bf16 v[236:239], v[132:135], v[232:235], v[236:239]
	v_mfma_f32_16x16x32_bf16 v[240:243], v[140:143], v[232:235], v[240:243]
	v_mfma_f32_16x16x32_bf16 v[244:247], v[148:151], v[232:235], v[244:247]
	v_mfma_f32_16x16x32_bf16 v[200:203], v[156:159], v[232:235], v[200:203]
	s_setprio 0
	s_barrier
; #define PG8_STAGE(bufoff, gbase, voff) do { _Pragma("unroll") for (int _i = 0; _i < 2; ++_i) \
;         __builtin_amdgcn_global_load_lds((const unsigned*)((const char*)(gbase) + (voff)[_i]), (PG8_LAS unsigned*)(lds + (bufoff) + ldsw + _i * 8192), 16, 0, 0); } while (0)
; #define PG8_LDA(dst, b, h) do { _Pragma("unroll") for (int m = 0; m < 4; ++m) _Pragma("unroll") for (int k = 0; k < 2; ++k) dst[m][k] = *(const PG8_LAS bf16x8*)(lds + PG8_SA(b, h) + aoff + m * 2048 + k * 1024); } while (0)
; #define PG8_MMA(ai, bj, At, Bt) do { __builtin_amdgcn_s_setprio(1); _Pragma("unroll") for (int m = 0; m < 4; ++m) _Pragma("unroll") for (int n = 0; n < 2; ++n) _Pragma("unroll") for (int k = 0; k < 2; ++k) \
;         acc[ai][bj][m][n] = __builtin_amdgcn_mfma_f32_16x16x32_bf16(Bt[n][k], At[m][k], acc[ai][bj][m][n], 0, 0, 0); __builtin_amdgcn_s_setprio(0); } while (0)
; #define PG8_WAIT_V(n) asm volatile("s_waitcnt vmcnt(" #n ")" ::: "memory")
; #define PG8_WAIT_L(n) asm volatile("s_waitcnt lgkmcnt(" #n ")" ::: "memory")
; #define PG8_BAR __builtin_amdgcn_s_barrier()
; #define PG8_SCHED __builtin_amdgcn_sched_barrier(0)
; template <class Epi, class Sched, bool ALIGN_EPI = false, bool SP2 = false>
; __device__ __forceinline__ void gemm_phase(PG8_LAS unsigned char* lds, const Gemm g, const Sched& S, const Epi& E) {
;     ...
;             PG8_LDA(At, 1, 1); PG8_STAGE(PG8_SB(1, 0), b3, voffB); PG8_STAGE(PG8_SB(1, 1), b3 + hstep, voffB); PG8_STAGE(PG8_SA(1, 0), a3, voffA);
;             PG8_WAIT_V(8); PG8_WAIT_L(0); PG8_BAR; PG8_MMA(1, 0, At, B0); PG8_MMA(1, 1, At, B1); PG8_BAR; PG8_SCHED;
	s_add_i32 s25, s25, s44
	s_add_u32 s98, s40, 0x80
	s_addc_u32 s99, s41, 0
	s_mov_b32 m0, s25
	ds_read_b128 v[160:163], v230 offset:49152
	ds_read_b128 v[164:167], v230 offset:50176
	ds_read_b128 v[168:171], v230 offset:51200
	ds_read_b128 v[172:175], v230 offset:52224
	ds_read_b128 v[176:179], v230 offset:53248
	ds_read_b128 v[180:183], v230 offset:54272
	ds_read_b128 v[204:207], v230 offset:55296
	ds_read_b128 v[208:211], v230 offset:56320
	global_load_lds_dwordx4 v184, s[98:99]
	s_add_i32 m0, s25, 0x2000
	s_add_u32 s100, s40, 0x40080
	s_addc_u32 s101, s41, 0
	s_add_i32 s94, s94, s44
	global_load_lds_dwordx4 v194, s[98:99]
	s_mov_b32 m0, s94
	s_add_u32 s98, s42, 0x80
	s_addc_u32 s99, s43, 0
	global_load_lds_dwordx4 v184, s[100:101]
	s_add_i32 m0, s94, 0x2000
	s_nop 0
	global_load_lds_dwordx4 v194, s[100:101]
	s_mov_b32 m0, s51
	s_nop 0
	global_load_lds_dwordx4 v198, s[98:99]
	s_mov_b32 m0, s52
	s_nop 0
	global_load_lds_dwordx4 v196, s[98:99]
	s_and_b32 m0, s44, 0xc00
	s_add_i32 m0, m0, 0x21800
	s_nop 0
	global_load_lds_dwordx4 v248, s[98:99]
	s_waitcnt vmcnt(9)
	s_waitcnt lgkmcnt(0)
	s_barrier
	s_setprio 1
	s_waitcnt lgkmcnt(0)
	v_mfma_f32_16x16x32_bf16 v[60:63], v[128:131], v[160:163], v[60:63]
	v_mfma_f32_16x16x32_bf16 v[56:59], v[136:139], v[160:163], v[56:59]
	v_mfma_f32_16x16x32_bf16 v[44:47], v[128:131], v[168:171], v[44:47]
	v_mfma_f32_16x16x32_bf16 v[40:43], v[136:139], v[168:171], v[40:43]
	v_mfma_f32_16x16x32_bf16 v[28:31], v[128:131], v[176:179], v[28:31]
	v_mfma_f32_16x16x32_bf16 v[24:27], v[136:139], v[176:179], v[24:27]
	v_mfma_f32_16x16x32_bf16 v[12:15], v[128:131], v[204:207], v[12:15]
	v_mfma_f32_16x16x32_bf16 v[8:11], v[136:139], v[204:207], v[8:11]
	v_mfma_f32_16x16x32_bf16 v[60:63], v[132:135], v[164:167], v[60:63]
	v_mfma_f32_16x16x32_bf16 v[56:59], v[140:143], v[164:167], v[56:59]
	v_mfma_f32_16x16x32_bf16 v[44:47], v[132:135], v[172:175], v[44:47]
	v_mfma_f32_16x16x32_bf16 v[40:43], v[140:143], v[172:175], v[40:43]
	v_mfma_f32_16x16x32_bf16 v[28:31], v[132:135], v[180:183], v[28:31]
	v_mfma_f32_16x16x32_bf16 v[24:27], v[140:143], v[180:183], v[24:27]
	v_mfma_f32_16x16x32_bf16 v[12:15], v[132:135], v[208:211], v[12:15]
	v_mfma_f32_16x16x32_bf16 v[8:11], v[140:143], v[208:211], v[8:11]
	s_setprio 0
	s_setprio 1
	v_mfma_f32_16x16x32_bf16 v[52:55], v[144:147], v[160:163], v[52:55]
	v_mfma_f32_16x16x32_bf16 v[48:51], v[152:155], v[160:163], v[48:51]
	v_mfma_f32_16x16x32_bf16 v[36:39], v[144:147], v[168:171], v[36:39]
	v_mfma_f32_16x16x32_bf16 v[32:35], v[152:155], v[168:171], v[32:35]
	v_mfma_f32_16x16x32_bf16 v[20:23], v[144:147], v[176:179], v[20:23]
	v_mfma_f32_16x16x32_bf16 v[16:19], v[152:155], v[176:179], v[16:19]
	v_mfma_f32_16x16x32_bf16 v[4:7], v[144:147], v[204:207], v[4:7]
	v_mfma_f32_16x16x32_bf16 v[0:3], v[152:155], v[204:207], v[0:3]
	v_mfma_f32_16x16x32_bf16 v[52:55], v[148:151], v[164:167], v[52:55]
	v_mfma_f32_16x16x32_bf16 v[48:51], v[156:159], v[164:167], v[48:51]
	v_mfma_f32_16x16x32_bf16 v[36:39], v[148:151], v[172:175], v[36:39]
	v_mfma_f32_16x16x32_bf16 v[32:35], v[156:159], v[172:175], v[32:35]
	v_mfma_f32_16x16x32_bf16 v[20:23], v[148:151], v[180:183], v[20:23]
	v_mfma_f32_16x16x32_bf16 v[16:19], v[156:159], v[180:183], v[16:19]
	v_mfma_f32_16x16x32_bf16 v[4:7], v[148:151], v[208:211], v[4:7]
	v_mfma_f32_16x16x32_bf16 v[0:3], v[156:159], v[208:211], v[0:3]
	s_setprio 0
	s_barrier
	s_add_i32 s93, s93, 2
	s_add_u32 s0, s0, 0x100
	s_addc_u32 s1, s1, 0
	s_add_u32 s59, s59, 0x100
	s_addc_u32 s92, s92, 0
	s_cmp_gt_u32 s93, 13
	s_cbranch_scc0 .LBB0_218
	s_and_b64 vcc, exec, s[20:21]
	s_cbranch_vccz .LBB0_221
	s_barrier

; #define PG8_STAGE(bufoff, gbase, voff) do { _Pragma("unroll") for (int _i = 0; _i < 2; ++_i) \
;         __builtin_amdgcn_global_load_lds((const unsigned*)((const char*)(gbase) + (voff)[_i]), (PG8_LAS unsigned*)(lds + (bufoff) + ldsw + _i * 8192), 16, 0, 0); } while (0)
; #define PG8_LDA(dst, b, h) do { _Pragma("unroll") for (int m = 0; m < 4; ++m) _Pragma("unroll") for (int k = 0; k < 2; ++k) dst[m][k] = *(const PG8_LAS bf16x8*)(lds + PG8_SA(b, h) + aoff + m * 2048 + k * 1024); } while (0)
; #define PG8_LDB(dst, b, h) do { _Pragma("unroll") for (int n = 0; n < 2; ++n) _Pragma("unroll") for (int k = 0; k < 2; ++k) dst[n][k] = *(const PG8_LAS bf16x8*)(lds + PG8_SB(b, h) + boff + n * 2048 + k * 1024); } while (0)
; #define PG8_MMA(ai, bj, At, Bt) do { __builtin_amdgcn_s_setprio(1); _Pragma("unroll") for (int m = 0; m < 4; ++m) _Pragma("unroll") for (int n = 0; n < 2; ++n) _Pragma("unroll") for (int k = 0; k < 2; ++k) \
;         acc[ai][bj][m][n] = __builtin_amdgcn_mfma_f32_16x16x32_bf16(Bt[n][k], At[m][k], acc[ai][bj][m][n], 0, 0, 0); __builtin_amdgcn_s_setprio(0); } while (0)
; #define PG8_WAIT_V(n) asm volatile("s_waitcnt vmcnt(" #n ")" ::: "memory")
; #define PG8_WAIT_L(n) asm volatile("s_waitcnt lgkmcnt(" #n ")" ::: "memory")
; #define PG8_BAR __builtin_amdgcn_s_barrier()
; #define PG8_SCHED __builtin_amdgcn_sched_barrier(0)
; template <class Epi, class Sched, bool ALIGN_EPI = false, bool SP2 = false>
; __device__ __forceinline__ void gemm_phase(PG8_LAS unsigned char* lds, const Gemm g, const Sched& S, const Epi& E) {
;     ...
;             PG8_LDB(B0, 0, 0); PG8_LDB(B1, 0, 1); PG8_SCHED; PG8_LDA(At, 0, 0); PG8_STAGE(PG8_SA(1, 1), a1 + hstep, voffA);
;             PG8_WAIT_V(8); PG8_WAIT_L(0); PG8_BAR; PG8_MMA(0, 0, At, B0); PG8_MMA(0, 1, At, B1); PG8_BAR; PG8_SCHED;
;             PG8_LDA(At, 0, 1); PG8_STAGE(PG8_SB(0, 0), b2, voffB); PG8_STAGE(PG8_SB(0, 1), b2 + hstep, voffB); PG8_STAGE(PG8_SA(0, 0), a2, voffA);
;             PG8_WAIT_V(8); PG8_WAIT_L(0); PG8_BAR; PG8_MMA(1, 0, At, B0); PG8_MMA(1, 1, At, B1); PG8_BAR; PG8_SCHED;
.LBB0_461:
	s_add_u32 s0, s22, 0x100
	s_addc_u32 s1, s23, 0
	s_cmp_eq_u32 s50, 40
	s_cselect_b32 s27, s19, s1
	s_cselect_b32 s26, s18, s0
	s_cselect_b32 s25, s21, s5
	s_cselect_b32 s24, s20, s4
	s_add_i32 s6, 0, 0x10000
	s_add_i32 s51, 0, 0x14000
	v_add_u32_e32 v140, s6, v228
	v_add_u32_e32 v156, s51, v228
	ds_read_b128 v[128:131], v140
	ds_read_b128 v[132:135], v140 offset:1024
	ds_read_b128 v[136:139], v140 offset:2048
	ds_read_b128 v[140:143], v140 offset:3072
	ds_read_b128 v[144:147], v156
	ds_read_b128 v[148:151], v156 offset:1024
	ds_read_b128 v[152:155], v156 offset:2048
	ds_read_b128 v[156:159], v156 offset:3072
	s_add_u32 s98, s22, 0xb0080
	s_addc_u32 s99, s23, 0
	s_add_i32 m0, s30, 0xc000
	ds_read_b128 v[160:163], v230
	ds_read_b128 v[164:167], v230 offset:1024
	ds_read_b128 v[168:171], v230 offset:2048
	ds_read_b128 v[172:175], v230 offset:3072
	ds_read_b128 v[176:179], v230 offset:4096
	ds_read_b128 v[180:183], v230 offset:5120
	ds_read_b128 v[204:207], v230 offset:6144
	ds_read_b128 v[208:211], v230 offset:7168
	ds_read_b128 v[212:215], v249
	ds_read_b128 v[232:235], v249 offset:1024
	global_load_lds_dwordx4 v198, s[98:99]
	s_add_i32 m0, s30, 0xe000
	s_nop 0
	global_load_lds_dwordx4 v196, s[98:99]
	s_nop 0
	s_waitcnt vmcnt(9)
	s_waitcnt lgkmcnt(0)
	s_barrier
	s_setprio 1
	s_waitcnt lgkmcnt(0)
	v_mfma_f32_16x16x32_bf16 v[124:127], v[128:131], v[160:163], v[124:127]
	v_mfma_f32_16x16x32_bf16 v[120:123], v[136:139], v[160:163], v[120:123]
	v_mfma_f32_16x16x32_bf16 v[108:111], v[128:131], v[168:171], v[108:111]
	v_mfma_f32_16x16x32_bf16 v[104:107], v[136:139], v[168:171], v[104:107]
	v_mfma_f32_16x16x32_bf16 v[92:95], v[128:131], v[176:179], v[92:95]
	v_mfma_f32_16x16x32_bf16 v[88:91], v[136:139], v[176:179], v[88:91]
	v_mfma_f32_16x16x32_bf16 v[76:79], v[128:131], v[204:207], v[76:79]
	v_mfma_f32_16x16x32_bf16 v[72:75], v[136:139], v[204:207], v[72:75]
	v_mfma_f32_16x16x32_bf16 v[124:127], v[132:135], v[164:167], v[124:127]
	v_mfma_f32_16x16x32_bf16 v[120:123], v[140:143], v[164:167], v[120:123]
	v_mfma_f32_16x16x32_bf16 v[108:111], v[132:135], v[172:175], v[108:111]
	v_mfma_f32_16x16x32_bf16 v[104:107], v[140:143], v[172:175], v[104:107]
	v_mfma_f32_16x16x32_bf16 v[92:95], v[132:135], v[180:183], v[92:95]
	v_mfma_f32_16x16x32_bf16 v[88:91], v[140:143], v[180:183], v[88:91]
	v_mfma_f32_16x16x32_bf16 v[76:79], v[132:135], v[208:211], v[76:79]
	v_mfma_f32_16x16x32_bf16 v[72:75], v[140:143], v[208:211], v[72:75]
	s_setprio 0
	s_setprio 1
	v_mfma_f32_16x16x32_bf16 v[116:119], v[144:147], v[160:163], v[116:119]
	v_mfma_f32_16x16x32_bf16 v[112:115], v[152:155], v[160:163], v[112:115]
	v_mfma_f32_16x16x32_bf16 v[100:103], v[144:147], v[168:171], v[100:103]
	v_mfma_f32_16x16x32_bf16 v[96:99], v[152:155], v[168:171], v[96:99]
	v_mfma_f32_16x16x32_bf16 v[84:87], v[144:147], v[176:179], v[84:87]
	v_mfma_f32_16x16x32_bf16 v[80:83], v[152:155], v[176:179], v[80:83]
	v_mfma_f32_16x16x32_bf16 v[68:71], v[144:147], v[204:207], v[68:71]
	v_mfma_f32_16x16x32_bf16 v[64:67], v[152:155], v[204:207], v[64:67]
	v_mfma_f32_16x16x32_bf16 v[116:119], v[148:151], v[164:167], v[116:119]
	v_mfma_f32_16x16x32_bf16 v[112:115], v[156:159], v[164:167], v[112:115]
	v_mfma_f32_16x16x32_bf16 v[100:103], v[148:151], v[172:175], v[100:103]
	v_mfma_f32_16x16x32_bf16 v[96:99], v[156:159], v[172:175], v[96:99]
	v_mfma_f32_16x16x32_bf16 v[84:87], v[148:151], v[180:183], v[84:87]
	v_mfma_f32_16x16x32_bf16 v[80:83], v[156:159], v[180:183], v[80:83]
	v_mfma_f32_16x16x32_bf16 v[68:71], v[148:151], v[208:211], v[68:71]
	v_mfma_f32_16x16x32_bf16 v[64:67], v[156:159], v[208:211], v[64:67]
	v_mfma_f32_16x16x32_bf16 v[236:239], v[128:131], v[212:215], v[236:239]
	v_mfma_f32_16x16x32_bf16 v[240:243], v[136:139], v[212:215], v[240:243]
	v_mfma_f32_16x16x32_bf16 v[244:247], v[144:147], v[212:215], v[244:247]
	v_mfma_f32_16x16x32_bf16 v[200:203], v[152:155], v[212:215], v[200:203]
	v_mfma_f32_16x16x32_bf16 v[236:239], v[132:135], v[232:235], v[236:239]
	v_mfma_f32_16x16x32_bf16 v[240:243], v[140:143], v[232:235], v[240:243]
	v_mfma_f32_16x16x32_bf16 v[244:247], v[148:151], v[232:235], v[244:247]
	v_mfma_f32_16x16x32_bf16 v[200:203], v[156:159], v[232:235], v[200:203]
	s_setprio 0
	s_barrier
	s_add_i32 s6, s6, s29
	s_mov_b32 m0, s6
	ds_read_b128 v[160:163], v230 offset:16384
	ds_read_b128 v[164:167], v230 offset:17408
	ds_read_b128 v[168:171], v230 offset:18432
	ds_read_b128 v[172:175], v230 offset:19456
	ds_read_b128 v[176:179], v230 offset:20480
	ds_read_b128 v[180:183], v230 offset:21504
	ds_read_b128 v[204:207], v230 offset:22528
	ds_read_b128 v[208:211], v230 offset:23552
	global_load_lds_dwordx4 v184, s[24:25]
	s_add_i32 m0, s6, 0x2000
	s_add_u32 s22, s24, 0xb0000
	s_addc_u32 s23, s25, 0
	s_add_i32 s6, s51, s29
	global_load_lds_dwordx4 v194, s[24:25]
	s_mov_b32 m0, s6
	s_nop 0
	global_load_lds_dwordx4 v184, s[22:23]
	s_add_i32 m0, s6, 0x2000
	s_nop 0
	global_load_lds_dwordx4 v194, s[22:23]
	s_mov_b32 m0, s30
	s_nop 0
	global_load_lds_dwordx4 v198, s[26:27]
	s_mov_b32 m0, s31
	s_nop 0
	global_load_lds_dwordx4 v196, s[26:27]
	s_and_b32 m0, s30, 0xc00
	s_add_i32 m0, m0, 0x20800
	s_nop 0
	global_load_lds_dwordx4 v248, s[26:27]
	s_nop 0
	s_waitcnt vmcnt(9)
	s_waitcnt lgkmcnt(0)
	s_barrier
; #define PG8_STAGE(bufoff, gbase, voff) do { _Pragma("unroll") for (int _i = 0; _i < 2; ++_i) \
;         __builtin_amdgcn_global_load_lds((const unsigned*)((const char*)(gbase) + (voff)[_i]), (PG8_LAS unsigned*)(lds + (bufoff) + ldsw + _i * 8192), 16, 0, 0); } while (0)
; #define PG8_LDA(dst, b, h) do { _Pragma("unroll") for (int m = 0; m < 4; ++m) _Pragma("unroll") for (int k = 0; k < 2; ++k) dst[m][k] = *(const PG8_LAS bf16x8*)(lds + PG8_SA(b, h) + aoff + m * 2048 + k * 1024); } while (0)
; #define PG8_LDB(dst, b, h) do { _Pragma("unroll") for (int n = 0; n < 2; ++n) _Pragma("unroll") for (int k = 0; k < 2; ++k) dst[n][k] = *(const PG8_LAS bf16x8*)(lds + PG8_SB(b, h) + boff + n * 2048 + k * 1024); } while (0)
; #define PG8_MMA(ai, bj, At, Bt) do { __builtin_amdgcn_s_setprio(1); _Pragma("unroll") for (int m = 0; m < 4; ++m) _Pragma("unroll") for (int n = 0; n < 2; ++n) _Pragma("unroll") for (int k = 0; k < 2; ++k) \
;         acc[ai][bj][m][n] = __builtin_amdgcn_mfma_f32_16x16x32_bf16(Bt[n][k], At[m][k], acc[ai][bj][m][n], 0, 0, 0); __builtin_amdgcn_s_setprio(0); } while (0)
; #define PG8_WAIT_V(n) asm volatile("s_waitcnt vmcnt(" #n ")" ::: "memory")
; #define PG8_WAIT_L(n) asm volatile("s_waitcnt lgkmcnt(" #n ")" ::: "memory")
; #define PG8_BAR __builtin_amdgcn_s_barrier()
; #define PG8_SCHED __builtin_amdgcn_sched_barrier(0)
; template <class Epi, class Sched, bool ALIGN_EPI = false, bool SP2 = false>
; __device__ __forceinline__ void gemm_phase(PG8_LAS unsigned char* lds, const Gemm g, const Sched& S, const Epi& E) {
;     ...
;             PG8_WAIT_V(8); PG8_WAIT_L(0); PG8_BAR; PG8_MMA(1, 0, At, B0); PG8_MMA(1, 1, At, B1); PG8_BAR; PG8_SCHED;
;             PG8_LDB(B0, 1, 0); PG8_LDB(B1, 1, 1); PG8_SCHED; PG8_LDA(At, 1, 0); PG8_STAGE(PG8_SA(0, 1), a2 + hstep, voffA);
;             PG8_WAIT_V(8); PG8_WAIT_L(0); PG8_BAR; PG8_MMA(0, 0, At, B0); PG8_MMA(0, 1, At, B1); PG8_BAR; PG8_SCHED;
	s_setprio 1
	s_waitcnt lgkmcnt(0)
	v_mfma_f32_16x16x32_bf16 v[60:63], v[128:131], v[160:163], v[60:63]
	v_mfma_f32_16x16x32_bf16 v[56:59], v[136:139], v[160:163], v[56:59]
	v_mfma_f32_16x16x32_bf16 v[44:47], v[128:131], v[168:171], v[44:47]
	v_mfma_f32_16x16x32_bf16 v[40:43], v[136:139], v[168:171], v[40:43]
	v_mfma_f32_16x16x32_bf16 v[28:31], v[128:131], v[176:179], v[28:31]
	v_mfma_f32_16x16x32_bf16 v[24:27], v[136:139], v[176:179], v[24:27]
	v_mfma_f32_16x16x32_bf16 v[12:15], v[128:131], v[204:207], v[12:15]
	v_mfma_f32_16x16x32_bf16 v[8:11], v[136:139], v[204:207], v[8:11]
	v_mfma_f32_16x16x32_bf16 v[60:63], v[132:135], v[164:167], v[60:63]
	v_mfma_f32_16x16x32_bf16 v[56:59], v[140:143], v[164:167], v[56:59]
	v_mfma_f32_16x16x32_bf16 v[44:47], v[132:135], v[172:175], v[44:47]
	v_mfma_f32_16x16x32_bf16 v[40:43], v[140:143], v[172:175], v[40:43]
	v_mfma_f32_16x16x32_bf16 v[28:31], v[132:135], v[180:183], v[28:31]
	v_mfma_f32_16x16x32_bf16 v[24:27], v[140:143], v[180:183], v[24:27]
	v_mfma_f32_16x16x32_bf16 v[12:15], v[132:135], v[208:211], v[12:15]
	v_mfma_f32_16x16x32_bf16 v[8:11], v[140:143], v[208:211], v[8:11]
	s_setprio 0
	s_setprio 1
	v_mfma_f32_16x16x32_bf16 v[52:55], v[144:147], v[160:163], v[52:55]
	v_mfma_f32_16x16x32_bf16 v[48:51], v[152:155], v[160:163], v[48:51]
	v_mfma_f32_16x16x32_bf16 v[36:39], v[144:147], v[168:171], v[36:39]
	v_mfma_f32_16x16x32_bf16 v[32:35], v[152:155], v[168:171], v[32:35]
	v_mfma_f32_16x16x32_bf16 v[20:23], v[144:147], v[176:179], v[20:23]
	v_mfma_f32_16x16x32_bf16 v[16:19], v[152:155], v[176:179], v[16:19]
	v_mfma_f32_16x16x32_bf16 v[4:7], v[144:147], v[204:207], v[4:7]
	v_mfma_f32_16x16x32_bf16 v[0:3], v[152:155], v[204:207], v[0:3]
	v_mfma_f32_16x16x32_bf16 v[52:55], v[148:151], v[164:167], v[52:55]
	v_mfma_f32_16x16x32_bf16 v[48:51], v[156:159], v[164:167], v[48:51]
	v_mfma_f32_16x16x32_bf16 v[36:39], v[148:151], v[172:175], v[36:39]
	v_mfma_f32_16x16x32_bf16 v[32:35], v[156:159], v[172:175], v[32:35]
	v_mfma_f32_16x16x32_bf16 v[20:23], v[148:151], v[180:183], v[20:23]
	v_mfma_f32_16x16x32_bf16 v[16:19], v[156:159], v[180:183], v[16:19]
	v_mfma_f32_16x16x32_bf16 v[4:7], v[148:151], v[208:211], v[4:7]
	v_mfma_f32_16x16x32_bf16 v[0:3], v[156:159], v[208:211], v[0:3]
	s_setprio 0
	s_barrier
	s_add_i32 s6, 0, 0x18000
	s_add_i32 s51, 0, 0x1c000
	v_add_u32_e32 v140, s6, v228
	v_add_u32_e32 v156, s51, v228
	ds_read_b128 v[128:131], v140
	ds_read_b128 v[132:135], v140 offset:1024
	ds_read_b128 v[136:139], v140 offset:2048
	ds_read_b128 v[140:143], v140 offset:3072
	ds_read_b128 v[144:147], v156
	ds_read_b128 v[148:151], v156 offset:1024
	ds_read_b128 v[152:155], v156 offset:2048
	ds_read_b128 v[156:159], v156 offset:3072
	s_add_u32 s22, s26, 0xb0000
	s_addc_u32 s23, s27, 0
	s_mov_b32 m0, s34
	ds_read_b128 v[160:163], v230 offset:32768
	ds_read_b128 v[164:167], v230 offset:33792
	ds_read_b128 v[168:171], v230 offset:34816
	ds_read_b128 v[172:175], v230 offset:35840
	ds_read_b128 v[176:179], v230 offset:36864
	ds_read_b128 v[180:183], v230 offset:37888
	ds_read_b128 v[204:207], v230 offset:38912
	ds_read_b128 v[208:211], v230 offset:39936
	ds_read_b128 v[212:215], v249 offset:4096
	ds_read_b128 v[232:235], v249 offset:5120
	global_load_lds_dwordx4 v198, s[22:23]
	s_mov_b32 m0, s40
	s_nop 0
	global_load_lds_dwordx4 v196, s[22:23]
	s_nop 0
	s_waitcnt vmcnt(9)
	s_waitcnt lgkmcnt(0)
	s_barrier
	s_setprio 1
	s_waitcnt lgkmcnt(0)
	v_mfma_f32_16x16x32_bf16 v[124:127], v[128:131], v[160:163], v[124:127]
	v_mfma_f32_16x16x32_bf16 v[120:123], v[136:139], v[160:163], v[120:123]
	v_mfma_f32_16x16x32_bf16 v[108:111], v[128:131], v[168:171], v[108:111]
	v_mfma_f32_16x16x32_bf16 v[104:107], v[136:139], v[168:171], v[104:107]
	v_mfma_f32_16x16x32_bf16 v[92:95], v[128:131], v[176:179], v[92:95]
	v_mfma_f32_16x16x32_bf16 v[88:91], v[136:139], v[176:179], v[88:91]
	v_mfma_f32_16x16x32_bf16 v[76:79], v[128:131], v[204:207], v[76:79]
	v_mfma_f32_16x16x32_bf16 v[72:75], v[136:139], v[204:207], v[72:75]
	v_mfma_f32_16x16x32_bf16 v[124:127], v[132:135], v[164:167], v[124:127]
	v_mfma_f32_16x16x32_bf16 v[120:123], v[140:143], v[164:167], v[120:123]
	v_mfma_f32_16x16x32_bf16 v[108:111], v[132:135], v[172:175], v[108:111]
	v_mfma_f32_16x16x32_bf16 v[104:107], v[140:143], v[172:175], v[104:107]
	v_mfma_f32_16x16x32_bf16 v[92:95], v[132:135], v[180:183], v[92:95]
	v_mfma_f32_16x16x32_bf16 v[88:91], v[140:143], v[180:183], v[88:91]
	v_mfma_f32_16x16x32_bf16 v[76:79], v[132:135], v[208:211], v[76:79]
	v_mfma_f32_16x16x32_bf16 v[72:75], v[140:143], v[208:211], v[72:75]
	s_setprio 0
	s_setprio 1
	v_mfma_f32_16x16x32_bf16 v[116:119], v[144:147], v[160:163], v[116:119]
	v_mfma_f32_16x16x32_bf16 v[112:115], v[152:155], v[160:163], v[112:115]
	v_mfma_f32_16x16x32_bf16 v[100:103], v[144:147], v[168:171], v[100:103]
	v_mfma_f32_16x16x32_bf16 v[96:99], v[152:155], v[168:171], v[96:99]
	v_mfma_f32_16x16x32_bf16 v[84:87], v[144:147], v[176:179], v[84:87]
	v_mfma_f32_16x16x32_bf16 v[80:83], v[152:155], v[176:179], v[80:83]
	v_mfma_f32_16x16x32_bf16 v[68:71], v[144:147], v[204:207], v[68:71]
	v_mfma_f32_16x16x32_bf16 v[64:67], v[152:155], v[204:207], v[64:67]
	v_mfma_f32_16x16x32_bf16 v[116:119], v[148:151], v[164:167], v[116:119]
	v_mfma_f32_16x16x32_bf16 v[112:115], v[156:159], v[164:167], v[112:115]
	v_mfma_f32_16x16x32_bf16 v[100:103], v[148:151], v[172:175], v[100:103]
	v_mfma_f32_16x16x32_bf16 v[96:99], v[156:159], v[172:175], v[96:99]
	v_mfma_f32_16x16x32_bf16 v[84:87], v[148:151], v[180:183], v[84:87]
	v_mfma_f32_16x16x32_bf16 v[80:83], v[156:159], v[180:183], v[80:83]
	v_mfma_f32_16x16x32_bf16 v[68:71], v[148:151], v[208:211], v[68:71]
	v_mfma_f32_16x16x32_bf16 v[64:67], v[156:159], v[208:211], v[64:67]
	v_mfma_f32_16x16x32_bf16 v[236:239], v[128:131], v[212:215], v[236:239]
	v_mfma_f32_16x16x32_bf16 v[240:243], v[136:139], v[212:215], v[240:243]
	v_mfma_f32_16x16x32_bf16 v[244:247], v[144:147], v[212:215], v[244:247]
	v_mfma_f32_16x16x32_bf16 v[200:203], v[152:155], v[212:215], v[200:203]
	v_mfma_f32_16x16x32_bf16 v[236:239], v[132:135], v[232:235], v[236:239]
	v_mfma_f32_16x16x32_bf16 v[240:243], v[140:143], v[232:235], v[240:243]
	v_mfma_f32_16x16x32_bf16 v[244:247], v[148:151], v[232:235], v[244:247]
	v_mfma_f32_16x16x32_bf16 v[200:203], v[156:159], v[232:235], v[200:203]
	s_setprio 0
	s_barrier
; #define PG8_STAGE(bufoff, gbase, voff) do { _Pragma("unroll") for (int _i = 0; _i < 2; ++_i) \
;         __builtin_amdgcn_global_load_lds((const unsigned*)((const char*)(gbase) + (voff)[_i]), (PG8_LAS unsigned*)(lds + (bufoff) + ldsw + _i * 8192), 16, 0, 0); } while (0)
; #define PG8_LDA(dst, b, h) do { _Pragma("unroll") for (int m = 0; m < 4; ++m) _Pragma("unroll") for (int k = 0; k < 2; ++k) dst[m][k] = *(const PG8_LAS bf16x8*)(lds + PG8_SA(b, h) + aoff + m * 2048 + k * 1024); } while (0)
; #define PG8_MMA(ai, bj, At, Bt) do { __builtin_amdgcn_s_setprio(1); _Pragma("unroll") for (int m = 0; m < 4; ++m) _Pragma("unroll") for (int n = 0; n < 2; ++n) _Pragma("unroll") for (int k = 0; k < 2; ++k) \
;         acc[ai][bj][m][n] = __builtin_amdgcn_mfma_f32_16x16x32_bf16(Bt[n][k], At[m][k], acc[ai][bj][m][n], 0, 0, 0); __builtin_amdgcn_s_setprio(0); } while (0)
; #define PG8_WAIT_V(n) asm volatile("s_waitcnt vmcnt(" #n ")" ::: "memory")
; #define PG8_WAIT_L(n) asm volatile("s_waitcnt lgkmcnt(" #n ")" ::: "memory")
; #define PG8_BAR __builtin_amdgcn_s_barrier()
; #define PG8_SCHED __builtin_amdgcn_sched_barrier(0)
; template <class Epi, class Sched, bool ALIGN_EPI = false, bool SP2 = false>
; __device__ __forceinline__ void gemm_phase(PG8_LAS unsigned char* lds, const Gemm g, const Sched& S, const Epi& E) {
;     ...
;             PG8_LDA(At, 1, 1); PG8_STAGE(PG8_SB(1, 0), b3, voffB); PG8_STAGE(PG8_SB(1, 1), b3 + hstep, voffB); PG8_STAGE(PG8_SA(1, 0), a3, voffA);
;             PG8_WAIT_V(8); PG8_WAIT_L(0); PG8_BAR; PG8_MMA(1, 0, At, B0); PG8_MMA(1, 1, At, B1); PG8_BAR; PG8_SCHED;
	s_add_i32 s22, s6, s29
	s_add_u32 s98, s24, 0x80
	s_addc_u32 s99, s25, 0
	s_mov_b32 m0, s22
	ds_read_b128 v[160:163], v230 offset:49152
	ds_read_b128 v[164:167], v230 offset:50176
	ds_read_b128 v[168:171], v230 offset:51200
	ds_read_b128 v[172:175], v230 offset:52224
	ds_read_b128 v[176:179], v230 offset:53248
	ds_read_b128 v[180:183], v230 offset:54272
	ds_read_b128 v[204:207], v230 offset:55296
	ds_read_b128 v[208:211], v230 offset:56320
	global_load_lds_dwordx4 v184, s[98:99]
	s_add_i32 m0, s22, 0x2000
	s_add_u32 s100, s24, 0xb0080
	s_addc_u32 s101, s25, 0
	s_add_i32 s22, s51, s29
	global_load_lds_dwordx4 v194, s[98:99]
	s_mov_b32 m0, s22
	s_add_u32 s98, s26, 0x80
	s_addc_u32 s99, s27, 0
	global_load_lds_dwordx4 v184, s[100:101]
	s_add_i32 m0, s22, 0x2000
	s_nop 0
	global_load_lds_dwordx4 v194, s[100:101]
	s_mov_b32 m0, s41
	s_nop 0
	global_load_lds_dwordx4 v198, s[98:99]
	s_mov_b32 m0, s42
	s_nop 0
	global_load_lds_dwordx4 v196, s[98:99]
	s_and_b32 m0, s30, 0xc00
	s_add_i32 m0, m0, 0x21800
	s_nop 0
	global_load_lds_dwordx4 v248, s[98:99]
	s_waitcnt vmcnt(9)
	s_waitcnt lgkmcnt(0)
	s_barrier
	s_setprio 1
	s_waitcnt lgkmcnt(0)
	v_mfma_f32_16x16x32_bf16 v[60:63], v[128:131], v[160:163], v[60:63]
	v_mfma_f32_16x16x32_bf16 v[56:59], v[136:139], v[160:163], v[56:59]
	v_mfma_f32_16x16x32_bf16 v[44:47], v[128:131], v[168:171], v[44:47]
	v_mfma_f32_16x16x32_bf16 v[40:43], v[136:139], v[168:171], v[40:43]
	v_mfma_f32_16x16x32_bf16 v[28:31], v[128:131], v[176:179], v[28:31]
	v_mfma_f32_16x16x32_bf16 v[24:27], v[136:139], v[176:179], v[24:27]
	v_mfma_f32_16x16x32_bf16 v[12:15], v[128:131], v[204:207], v[12:15]
	v_mfma_f32_16x16x32_bf16 v[8:11], v[136:139], v[204:207], v[8:11]
	v_mfma_f32_16x16x32_bf16 v[60:63], v[132:135], v[164:167], v[60:63]
	v_mfma_f32_16x16x32_bf16 v[56:59], v[140:143], v[164:167], v[56:59]
	v_mfma_f32_16x16x32_bf16 v[44:47], v[132:135], v[172:175], v[44:47]
	v_mfma_f32_16x16x32_bf16 v[40:43], v[140:143], v[172:175], v[40:43]
	v_mfma_f32_16x16x32_bf16 v[28:31], v[132:135], v[180:183], v[28:31]
	v_mfma_f32_16x16x32_bf16 v[24:27], v[140:143], v[180:183], v[24:27]
	v_mfma_f32_16x16x32_bf16 v[12:15], v[132:135], v[208:211], v[12:15]
	v_mfma_f32_16x16x32_bf16 v[8:11], v[140:143], v[208:211], v[8:11]
	s_setprio 0
	s_setprio 1
	v_mfma_f32_16x16x32_bf16 v[52:55], v[144:147], v[160:163], v[52:55]
	v_mfma_f32_16x16x32_bf16 v[48:51], v[152:155], v[160:163], v[48:51]
	v_mfma_f32_16x16x32_bf16 v[36:39], v[144:147], v[168:171], v[36:39]
	v_mfma_f32_16x16x32_bf16 v[32:35], v[152:155], v[168:171], v[32:35]
	v_mfma_f32_16x16x32_bf16 v[20:23], v[144:147], v[176:179], v[20:23]
	v_mfma_f32_16x16x32_bf16 v[16:19], v[152:155], v[176:179], v[16:19]
	v_mfma_f32_16x16x32_bf16 v[4:7], v[144:147], v[204:207], v[4:7]
	v_mfma_f32_16x16x32_bf16 v[0:3], v[152:155], v[204:207], v[0:3]
	v_mfma_f32_16x16x32_bf16 v[52:55], v[148:151], v[164:167], v[52:55]
	v_mfma_f32_16x16x32_bf16 v[48:51], v[156:159], v[164:167], v[48:51]
	v_mfma_f32_16x16x32_bf16 v[36:39], v[148:151], v[172:175], v[36:39]
	v_mfma_f32_16x16x32_bf16 v[32:35], v[156:159], v[172:175], v[32:35]
	v_mfma_f32_16x16x32_bf16 v[20:23], v[148:151], v[180:183], v[20:23]
	v_mfma_f32_16x16x32_bf16 v[16:19], v[156:159], v[180:183], v[16:19]
	v_mfma_f32_16x16x32_bf16 v[4:7], v[148:151], v[208:211], v[4:7]
	v_mfma_f32_16x16x32_bf16 v[0:3], v[156:159], v[208:211], v[0:3]
	s_setprio 0
	s_barrier
	s_add_i32 s50, s50, 2
	s_add_u32 s4, s4, 0x100
	s_addc_u32 s5, s5, 0
	s_cmp_gt_u32 s50, 41
	s_mov_b64 s[22:23], s[0:1]
	s_cbranch_scc0 .LBB0_461
	s_and_b64 vcc, exec, s[16:17]
	s_cbranch_vccz .LBB0_464
	s_barrier

; #define PG8_STAGE(bufoff, gbase, voff) do { _Pragma("unroll") for (int _i = 0; _i < 2; ++_i) \
;         __builtin_amdgcn_global_load_lds((const unsigned*)((const char*)(gbase) + (voff)[_i]), (PG8_LAS unsigned*)(lds + (bufoff) + ldsw + _i * 8192), 16, 0, 0); } while (0)
; #define PG8_LDA(dst, b, h) do { _Pragma("unroll") for (int m = 0; m < 4; ++m) _Pragma("unroll") for (int k = 0; k < 2; ++k) dst[m][k] = *(const PG8_LAS bf16x8*)(lds + PG8_SA(b, h) + aoff + m * 2048 + k * 1024); } while (0)
; #define PG8_LDB(dst, b, h) do { _Pragma("unroll") for (int n = 0; n < 2; ++n) _Pragma("unroll") for (int k = 0; k < 2; ++k) dst[n][k] = *(const PG8_LAS bf16x8*)(lds + PG8_SB(b, h) + boff + n * 2048 + k * 1024); } while (0)
; #define PG8_MMA(ai, bj, At, Bt) do { __builtin_amdgcn_s_setprio(1); _Pragma("unroll") for (int m = 0; m < 4; ++m) _Pragma("unroll") for (int n = 0; n < 2; ++n) _Pragma("unroll") for (int k = 0; k < 2; ++k) \
;         acc[ai][bj][m][n] = __builtin_amdgcn_mfma_f32_16x16x32_bf16(Bt[n][k], At[m][k], acc[ai][bj][m][n], 0, 0, 0); __builtin_amdgcn_s_setprio(0); } while (0)
; #define PG8_WAIT_V(n) asm volatile("s_waitcnt vmcnt(" #n ")" ::: "memory")
; #define PG8_WAIT_L(n) asm volatile("s_waitcnt lgkmcnt(" #n ")" ::: "memory")
; #define PG8_BAR __builtin_amdgcn_s_barrier()
; #define PG8_SCHED __builtin_amdgcn_sched_barrier(0)
; template <class Epi, class Sched, bool ALIGN_EPI = false, bool SP2 = false>
; __device__ __forceinline__ void gemm_phase(PG8_LAS unsigned char* lds, const Gemm g, const Sched& S, const Epi& E) {
;     ...
;             PG8_LDB(B0, 0, 0); PG8_LDB(B1, 0, 1); PG8_SCHED; PG8_LDA(At, 0, 0); PG8_STAGE(PG8_SA(1, 1), a1 + hstep, voffA);
;             PG8_WAIT_V(8); PG8_WAIT_L(0); PG8_BAR; PG8_MMA(0, 0, At, B0); PG8_MMA(0, 1, At, B1); PG8_BAR; PG8_SCHED;
;             PG8_LDA(At, 0, 1); PG8_STAGE(PG8_SB(0, 0), b2, voffB); PG8_STAGE(PG8_SB(0, 1), b2 + hstep, voffB); PG8_STAGE(PG8_SA(0, 0), a2, voffA);
;             PG8_WAIT_V(8); PG8_WAIT_L(0); PG8_BAR; PG8_MMA(1, 0, At, B0); PG8_MMA(1, 1, At, B1); PG8_BAR; PG8_SCHED;
.LBB0_509:
	s_add_u32 s2, s0, 0xfffc0080
	s_addc_u32 s3, s1, -1
	s_add_i32 s41, 0, 0x10000
	s_cmp_eq_u32 s40, 12
	s_cselect_b32 s9, s4, s3
	s_cselect_b32 s8, s5, s2
	v_add_u32_e32 v155, s41, v147
	s_cselect_b32 s3, s11, s39
	s_cselect_b32 s2, s24, s25
	s_add_i32 s46, 0, 0x14000
	ds_read_b128 v[128:131], v155
	ds_read_b128 v[132:135], v155 offset:1024
	ds_read_b128 v[156:159], v155 offset:2048
	ds_read_b128 v[170:173], v155 offset:3072
	v_add_u32_e32 v155, s46, v147
	ds_read_b128 v[174:177], v155
	ds_read_b128 v[178:181], v155 offset:1024
	ds_read_b128 v[194:197], v155 offset:2048
	ds_read_b128 v[198:201], v155 offset:3072
	v_lshl_add_u64 v[160:161], s[0:1], 0, v[150:151]
	s_add_i32 m0, s27, 0xc000
	ds_read_b128 v[202:205], v168
	ds_read_b128 v[206:209], v168 offset:1024
	ds_read_b128 v[210:213], v168 offset:2048
	ds_read_b128 v[228:231], v168 offset:3072
	ds_read_b128 v[232:235], v168 offset:4096
	ds_read_b128 v[236:239], v168 offset:5120
	ds_read_b128 v[240:243], v168 offset:6144
	ds_read_b128 v[244:247], v168 offset:7168
	global_load_lds_dwordx4 v[160:161], off
	v_lshl_add_u64 v[160:161], s[0:1], 0, v[152:153]
	s_add_i32 m0, s27, 0xe000
	s_nop 0
	global_load_lds_dwordx4 v[160:161], off
	s_nop 0
	s_waitcnt vmcnt(8)
	s_waitcnt lgkmcnt(0)
	s_barrier
	s_setprio 1
	s_waitcnt lgkmcnt(0)
	v_mfma_f32_16x16x32_bf16 v[124:127], v[128:131], v[202:205], v[124:127]
	v_mfma_f32_16x16x32_bf16 v[120:123], v[156:159], v[202:205], v[120:123]
	v_mfma_f32_16x16x32_bf16 v[108:111], v[128:131], v[210:213], v[108:111]
	v_mfma_f32_16x16x32_bf16 v[104:107], v[156:159], v[210:213], v[104:107]
	v_mfma_f32_16x16x32_bf16 v[92:95], v[128:131], v[232:235], v[92:95]
	v_mfma_f32_16x16x32_bf16 v[88:91], v[156:159], v[232:235], v[88:91]
	v_mfma_f32_16x16x32_bf16 v[76:79], v[128:131], v[240:243], v[76:79]
	v_mfma_f32_16x16x32_bf16 v[72:75], v[156:159], v[240:243], v[72:75]
	v_mfma_f32_16x16x32_bf16 v[124:127], v[132:135], v[206:209], v[124:127]
	v_mfma_f32_16x16x32_bf16 v[120:123], v[170:173], v[206:209], v[120:123]
	v_mfma_f32_16x16x32_bf16 v[108:111], v[132:135], v[228:231], v[108:111]
	v_mfma_f32_16x16x32_bf16 v[104:107], v[170:173], v[228:231], v[104:107]
	v_mfma_f32_16x16x32_bf16 v[92:95], v[132:135], v[236:239], v[92:95]
	v_mfma_f32_16x16x32_bf16 v[88:91], v[170:173], v[236:239], v[88:91]
	v_mfma_f32_16x16x32_bf16 v[76:79], v[132:135], v[244:247], v[76:79]
	v_mfma_f32_16x16x32_bf16 v[72:75], v[170:173], v[244:247], v[72:75]
	s_setprio 0
	s_setprio 1
	v_mfma_f32_16x16x32_bf16 v[116:119], v[174:177], v[202:205], v[116:119]
	v_mfma_f32_16x16x32_bf16 v[112:115], v[194:197], v[202:205], v[112:115]
	v_mfma_f32_16x16x32_bf16 v[100:103], v[174:177], v[210:213], v[100:103]
	v_mfma_f32_16x16x32_bf16 v[96:99], v[194:197], v[210:213], v[96:99]
	v_mfma_f32_16x16x32_bf16 v[84:87], v[174:177], v[232:235], v[84:87]
	v_mfma_f32_16x16x32_bf16 v[80:83], v[194:197], v[232:235], v[80:83]
	v_mfma_f32_16x16x32_bf16 v[68:71], v[174:177], v[240:243], v[68:71]
	v_mfma_f32_16x16x32_bf16 v[64:67], v[194:197], v[240:243], v[64:67]
	v_mfma_f32_16x16x32_bf16 v[116:119], v[178:181], v[206:209], v[116:119]
	v_mfma_f32_16x16x32_bf16 v[112:115], v[198:201], v[206:209], v[112:115]
	v_mfma_f32_16x16x32_bf16 v[100:103], v[178:181], v[228:231], v[100:103]
	v_mfma_f32_16x16x32_bf16 v[96:99], v[198:201], v[228:231], v[96:99]
	v_mfma_f32_16x16x32_bf16 v[84:87], v[178:181], v[236:239], v[84:87]
	v_mfma_f32_16x16x32_bf16 v[80:83], v[198:201], v[236:239], v[80:83]
	v_mfma_f32_16x16x32_bf16 v[68:71], v[178:181], v[244:247], v[68:71]
	v_mfma_f32_16x16x32_bf16 v[64:67], v[198:201], v[244:247], v[64:67]
	s_setprio 0
	s_barrier
	s_add_i32 s41, s41, s26
	v_lshl_add_u64 v[160:161], s[2:3], 0, v[140:141]
	s_mov_b32 m0, s41
	ds_read_b128 v[202:205], v168 offset:16384
	ds_read_b128 v[206:209], v168 offset:17408
	ds_read_b128 v[210:213], v168 offset:18432
	ds_read_b128 v[228:231], v168 offset:19456
	ds_read_b128 v[232:235], v168 offset:20480
	ds_read_b128 v[236:239], v168 offset:21504
	ds_read_b128 v[240:243], v168 offset:22528
	ds_read_b128 v[244:247], v168 offset:23552
	global_load_lds_dwordx4 v[160:161], off
	s_add_i32 m0, s41, 0x2000
	s_add_u32 s44, s2, 0x40000
	v_lshl_add_u64 v[182:183], s[2:3], 0, v[136:137]
	s_addc_u32 s45, s3, 0
	s_add_i32 s41, s46, s26
	global_load_lds_dwordx4 v[182:183], off
	v_lshl_add_u64 v[214:215], s[44:45], 0, v[140:141]
	s_mov_b32 m0, s41
	v_lshl_add_u64 v[248:249], s[8:9], 0, v[138:139]
	global_load_lds_dwordx4 v[214:215], off
	v_lshl_add_u64 v[214:215], s[44:45], 0, v[136:137]
	s_add_i32 m0, s41, 0x2000
	s_nop 0
	global_load_lds_dwordx4 v[214:215], off
	v_lshl_add_u64 v[214:215], s[8:9], 0, v[142:143]
	s_mov_b32 m0, s27
	s_nop 0
	global_load_lds_dwordx4 v[214:215], off
	s_mov_b32 m0, s28
	s_nop 0
	global_load_lds_dwordx4 v[248:249], off
	s_nop 0
	s_waitcnt vmcnt(8)
	s_waitcnt lgkmcnt(0)
	s_barrier
; #define PG8_STAGE(bufoff, gbase, voff) do { _Pragma("unroll") for (int _i = 0; _i < 2; ++_i) \
;         __builtin_amdgcn_global_load_lds((const unsigned*)((const char*)(gbase) + (voff)[_i]), (PG8_LAS unsigned*)(lds + (bufoff) + ldsw + _i * 8192), 16, 0, 0); } while (0)
; #define PG8_LDA(dst, b, h) do { _Pragma("unroll") for (int m = 0; m < 4; ++m) _Pragma("unroll") for (int k = 0; k < 2; ++k) dst[m][k] = *(const PG8_LAS bf16x8*)(lds + PG8_SA(b, h) + aoff + m * 2048 + k * 1024); } while (0)
; #define PG8_LDB(dst, b, h) do { _Pragma("unroll") for (int n = 0; n < 2; ++n) _Pragma("unroll") for (int k = 0; k < 2; ++k) dst[n][k] = *(const PG8_LAS bf16x8*)(lds + PG8_SB(b, h) + boff + n * 2048 + k * 1024); } while (0)
; #define PG8_MMA(ai, bj, At, Bt) do { __builtin_amdgcn_s_setprio(1); _Pragma("unroll") for (int m = 0; m < 4; ++m) _Pragma("unroll") for (int n = 0; n < 2; ++n) _Pragma("unroll") for (int k = 0; k < 2; ++k) \
;         acc[ai][bj][m][n] = __builtin_amdgcn_mfma_f32_16x16x32_bf16(Bt[n][k], At[m][k], acc[ai][bj][m][n], 0, 0, 0); __builtin_amdgcn_s_setprio(0); } while (0)
; #define PG8_WAIT_V(n) asm volatile("s_waitcnt vmcnt(" #n ")" ::: "memory")
; #define PG8_WAIT_L(n) asm volatile("s_waitcnt lgkmcnt(" #n ")" ::: "memory")
; #define PG8_BAR __builtin_amdgcn_s_barrier()
; #define PG8_SCHED __builtin_amdgcn_sched_barrier(0)
; template <class Epi, class Sched, bool ALIGN_EPI = false, bool SP2 = false>
; __device__ __forceinline__ void gemm_phase(PG8_LAS unsigned char* lds, const Gemm g, const Sched& S, const Epi& E) {
;     ...
;             PG8_WAIT_V(8); PG8_WAIT_L(0); PG8_BAR; PG8_MMA(1, 0, At, B0); PG8_MMA(1, 1, At, B1); PG8_BAR; PG8_SCHED;
;             PG8_LDB(B0, 1, 0); PG8_LDB(B1, 1, 1); PG8_SCHED; PG8_LDA(At, 1, 0); PG8_STAGE(PG8_SA(0, 1), a2 + hstep, voffA);
;             PG8_WAIT_V(8); PG8_WAIT_L(0); PG8_BAR; PG8_MMA(0, 0, At, B0); PG8_MMA(0, 1, At, B1); PG8_BAR; PG8_SCHED;
	s_setprio 1
	s_waitcnt lgkmcnt(0)
	v_mfma_f32_16x16x32_bf16 v[60:63], v[128:131], v[202:205], v[60:63]
	v_mfma_f32_16x16x32_bf16 v[56:59], v[156:159], v[202:205], v[56:59]
	v_mfma_f32_16x16x32_bf16 v[44:47], v[128:131], v[210:213], v[44:47]
	v_mfma_f32_16x16x32_bf16 v[40:43], v[156:159], v[210:213], v[40:43]
	v_mfma_f32_16x16x32_bf16 v[28:31], v[128:131], v[232:235], v[28:31]
	v_mfma_f32_16x16x32_bf16 v[24:27], v[156:159], v[232:235], v[24:27]
	v_mfma_f32_16x16x32_bf16 v[12:15], v[128:131], v[240:243], v[12:15]
	v_mfma_f32_16x16x32_bf16 v[8:11], v[156:159], v[240:243], v[8:11]
	v_mfma_f32_16x16x32_bf16 v[60:63], v[132:135], v[206:209], v[60:63]
	v_mfma_f32_16x16x32_bf16 v[56:59], v[170:173], v[206:209], v[56:59]
	v_mfma_f32_16x16x32_bf16 v[44:47], v[132:135], v[228:231], v[44:47]
	v_mfma_f32_16x16x32_bf16 v[40:43], v[170:173], v[228:231], v[40:43]
	v_mfma_f32_16x16x32_bf16 v[28:31], v[132:135], v[236:239], v[28:31]
	v_mfma_f32_16x16x32_bf16 v[24:27], v[170:173], v[236:239], v[24:27]
	v_mfma_f32_16x16x32_bf16 v[12:15], v[132:135], v[244:247], v[12:15]
	v_mfma_f32_16x16x32_bf16 v[8:11], v[170:173], v[244:247], v[8:11]
	s_setprio 0
	s_setprio 1
	v_mfma_f32_16x16x32_bf16 v[52:55], v[174:177], v[202:205], v[52:55]
	v_mfma_f32_16x16x32_bf16 v[48:51], v[194:197], v[202:205], v[48:51]
	v_mfma_f32_16x16x32_bf16 v[36:39], v[174:177], v[210:213], v[36:39]
	v_mfma_f32_16x16x32_bf16 v[32:35], v[194:197], v[210:213], v[32:35]
	v_mfma_f32_16x16x32_bf16 v[20:23], v[174:177], v[232:235], v[20:23]
	v_mfma_f32_16x16x32_bf16 v[16:19], v[194:197], v[232:235], v[16:19]
	v_mfma_f32_16x16x32_bf16 v[4:7], v[174:177], v[240:243], v[4:7]
	v_mfma_f32_16x16x32_bf16 v[0:3], v[194:197], v[240:243], v[0:3]
	v_mfma_f32_16x16x32_bf16 v[52:55], v[178:181], v[206:209], v[52:55]
	v_mfma_f32_16x16x32_bf16 v[48:51], v[198:201], v[206:209], v[48:51]
	v_mfma_f32_16x16x32_bf16 v[36:39], v[178:181], v[228:231], v[36:39]
	v_mfma_f32_16x16x32_bf16 v[32:35], v[198:201], v[228:231], v[32:35]
	v_mfma_f32_16x16x32_bf16 v[20:23], v[178:181], v[236:239], v[20:23]
	v_mfma_f32_16x16x32_bf16 v[16:19], v[198:201], v[236:239], v[16:19]
	v_mfma_f32_16x16x32_bf16 v[4:7], v[178:181], v[244:247], v[4:7]
	v_mfma_f32_16x16x32_bf16 v[0:3], v[198:201], v[244:247], v[0:3]
	s_setprio 0
	s_barrier
	s_add_i32 s41, 0, 0x18000
	v_add_u32_e32 v155, s41, v147
	s_add_i32 s44, 0, 0x1c000
	ds_read_b128 v[128:131], v155
	ds_read_b128 v[132:135], v155 offset:1024
	ds_read_b128 v[156:159], v155 offset:2048
	ds_read_b128 v[170:173], v155 offset:3072
	v_add_u32_e32 v155, s44, v147
	ds_read_b128 v[174:177], v155
	ds_read_b128 v[178:181], v155 offset:1024
	ds_read_b128 v[194:197], v155 offset:2048
	ds_read_b128 v[198:201], v155 offset:3072
	s_add_u32 s8, s8, 0x40000
	s_addc_u32 s9, s9, 0
	s_mov_b32 m0, s29
	v_lshl_add_u64 v[224:225], s[8:9], 0, v[142:143]
	ds_read_b128 v[202:205], v168 offset:32768
	ds_read_b128 v[206:209], v168 offset:33792
	ds_read_b128 v[210:213], v168 offset:34816
	ds_read_b128 v[228:231], v168 offset:35840
	ds_read_b128 v[232:235], v168 offset:36864
	ds_read_b128 v[236:239], v168 offset:37888
	ds_read_b128 v[240:243], v168 offset:38912
	ds_read_b128 v[244:247], v168 offset:39936
	global_load_lds_dwordx4 v[224:225], off
	v_lshl_add_u64 v[224:225], s[8:9], 0, v[138:139]
	s_mov_b32 m0, s30
	s_nop 0
	global_load_lds_dwordx4 v[224:225], off
	s_nop 0
	s_waitcnt vmcnt(8)
	s_waitcnt lgkmcnt(0)
	s_barrier
	s_setprio 1
	s_waitcnt lgkmcnt(0)
	v_mfma_f32_16x16x32_bf16 v[124:127], v[128:131], v[202:205], v[124:127]
	v_mfma_f32_16x16x32_bf16 v[120:123], v[156:159], v[202:205], v[120:123]
	v_mfma_f32_16x16x32_bf16 v[108:111], v[128:131], v[210:213], v[108:111]
	v_mfma_f32_16x16x32_bf16 v[104:107], v[156:159], v[210:213], v[104:107]
	v_mfma_f32_16x16x32_bf16 v[92:95], v[128:131], v[232:235], v[92:95]
	v_mfma_f32_16x16x32_bf16 v[88:91], v[156:159], v[232:235], v[88:91]
	v_mfma_f32_16x16x32_bf16 v[76:79], v[128:131], v[240:243], v[76:79]
	v_mfma_f32_16x16x32_bf16 v[72:75], v[156:159], v[240:243], v[72:75]
	v_mfma_f32_16x16x32_bf16 v[124:127], v[132:135], v[206:209], v[124:127]
	v_mfma_f32_16x16x32_bf16 v[120:123], v[170:173], v[206:209], v[120:123]
	v_mfma_f32_16x16x32_bf16 v[108:111], v[132:135], v[228:231], v[108:111]
	v_mfma_f32_16x16x32_bf16 v[104:107], v[170:173], v[228:231], v[104:107]
	v_mfma_f32_16x16x32_bf16 v[92:95], v[132:135], v[236:239], v[92:95]
	v_mfma_f32_16x16x32_bf16 v[88:91], v[170:173], v[236:239], v[88:91]
	v_mfma_f32_16x16x32_bf16 v[76:79], v[132:135], v[244:247], v[76:79]
	v_mfma_f32_16x16x32_bf16 v[72:75], v[170:173], v[244:247], v[72:75]
	s_setprio 0
	s_setprio 1
	v_mfma_f32_16x16x32_bf16 v[116:119], v[174:177], v[202:205], v[116:119]
	v_mfma_f32_16x16x32_bf16 v[112:115], v[194:197], v[202:205], v[112:115]
	v_mfma_f32_16x16x32_bf16 v[100:103], v[174:177], v[210:213], v[100:103]
	v_mfma_f32_16x16x32_bf16 v[96:99], v[194:197], v[210:213], v[96:99]
	v_mfma_f32_16x16x32_bf16 v[84:87], v[174:177], v[232:235], v[84:87]
	v_mfma_f32_16x16x32_bf16 v[80:83], v[194:197], v[232:235], v[80:83]
	v_mfma_f32_16x16x32_bf16 v[68:71], v[174:177], v[240:243], v[68:71]
	v_mfma_f32_16x16x32_bf16 v[64:67], v[194:197], v[240:243], v[64:67]
	v_mfma_f32_16x16x32_bf16 v[116:119], v[178:181], v[206:209], v[116:119]
	v_mfma_f32_16x16x32_bf16 v[112:115], v[198:201], v[206:209], v[112:115]
	v_mfma_f32_16x16x32_bf16 v[100:103], v[178:181], v[228:231], v[100:103]
	v_mfma_f32_16x16x32_bf16 v[96:99], v[198:201], v[228:231], v[96:99]
	v_mfma_f32_16x16x32_bf16 v[84:87], v[178:181], v[236:239], v[84:87]
	v_mfma_f32_16x16x32_bf16 v[80:83], v[198:201], v[236:239], v[80:83]
	v_mfma_f32_16x16x32_bf16 v[68:71], v[178:181], v[244:247], v[68:71]
	v_mfma_f32_16x16x32_bf16 v[64:67], v[198:201], v[244:247], v[64:67]
	s_setprio 0
	s_barrier
; #define PG8_STAGE(bufoff, gbase, voff) do { _Pragma("unroll") for (int _i = 0; _i < 2; ++_i) \
;         __builtin_amdgcn_global_load_lds((const unsigned*)((const char*)(gbase) + (voff)[_i]), (PG8_LAS unsigned*)(lds + (bufoff) + ldsw + _i * 8192), 16, 0, 0); } while (0)
; #define PG8_LDA(dst, b, h) do { _Pragma("unroll") for (int m = 0; m < 4; ++m) _Pragma("unroll") for (int k = 0; k < 2; ++k) dst[m][k] = *(const PG8_LAS bf16x8*)(lds + PG8_SA(b, h) + aoff + m * 2048 + k * 1024); } while (0)
; #define PG8_MMA(ai, bj, At, Bt) do { __builtin_amdgcn_s_setprio(1); _Pragma("unroll") for (int m = 0; m < 4; ++m) _Pragma("unroll") for (int n = 0; n < 2; ++n) _Pragma("unroll") for (int k = 0; k < 2; ++k) \
;         acc[ai][bj][m][n] = __builtin_amdgcn_mfma_f32_16x16x32_bf16(Bt[n][k], At[m][k], acc[ai][bj][m][n], 0, 0, 0); __builtin_amdgcn_s_setprio(0); } while (0)
; #define PG8_WAIT_V(n) asm volatile("s_waitcnt vmcnt(" #n ")" ::: "memory")
; #define PG8_WAIT_L(n) asm volatile("s_waitcnt lgkmcnt(" #n ")" ::: "memory")
; #define PG8_BAR __builtin_amdgcn_s_barrier()
; #define PG8_SCHED __builtin_amdgcn_sched_barrier(0)
; template <class Epi, class Sched, bool ALIGN_EPI = false, bool SP2 = false>
; __device__ __forceinline__ void gemm_phase(PG8_LAS unsigned char* lds, const Gemm g, const Sched& S, const Epi& E) {
;     ...
;             PG8_LDA(At, 1, 1); PG8_STAGE(PG8_SB(1, 0), b3, voffB); PG8_STAGE(PG8_SB(1, 1), b3 + hstep, voffB); PG8_STAGE(PG8_SA(1, 0), a3, voffA);
;             PG8_WAIT_V(8); PG8_WAIT_L(0); PG8_BAR; PG8_MMA(1, 0, At, B0); PG8_MMA(1, 1, At, B1); PG8_BAR; PG8_SCHED;
;     ...
;         if constexpr (ALIGN_EPI) { if (wr == 0) PG8_BAR; }
	s_add_i32 s8, s41, s26
	v_lshl_add_u64 v[160:161], v[160:161], 0, s[96:97]
	s_mov_b32 m0, s8
	ds_read_b128 v[202:205], v168 offset:49152
	ds_read_b128 v[206:209], v168 offset:50176
	ds_read_b128 v[210:213], v168 offset:51200
	ds_read_b128 v[228:231], v168 offset:52224
	ds_read_b128 v[232:235], v168 offset:53248
	ds_read_b128 v[236:239], v168 offset:54272
	ds_read_b128 v[240:243], v168 offset:55296
	ds_read_b128 v[244:247], v168 offset:56320
	global_load_lds_dwordx4 v[160:161], off
	s_add_i32 m0, s8, 0x2000
	s_add_u32 s2, s2, 0x40080
	v_lshl_add_u64 v[160:161], v[182:183], 0, s[96:97]
	s_addc_u32 s3, s3, 0
	s_add_i32 s8, s44, s26
	global_load_lds_dwordx4 v[160:161], off
	v_lshl_add_u64 v[160:161], s[2:3], 0, v[140:141]
	s_mov_b32 m0, s8
	s_nop 0
	global_load_lds_dwordx4 v[160:161], off
	v_lshl_add_u64 v[160:161], s[2:3], 0, v[136:137]
	s_add_i32 m0, s8, 0x2000
	s_nop 0
	global_load_lds_dwordx4 v[160:161], off
	v_lshl_add_u64 v[160:161], v[214:215], 0, s[96:97]
	s_mov_b32 m0, s31
	s_nop 0
	global_load_lds_dwordx4 v[160:161], off
	v_lshl_add_u64 v[160:161], v[248:249], 0, s[96:97]
	s_mov_b32 m0, s34
	s_nop 0
	global_load_lds_dwordx4 v[160:161], off
	s_waitcnt vmcnt(8)
	s_waitcnt lgkmcnt(0)
	s_barrier
	s_setprio 1
	s_waitcnt lgkmcnt(0)
	v_mfma_f32_16x16x32_bf16 v[60:63], v[128:131], v[202:205], v[60:63]
	v_mfma_f32_16x16x32_bf16 v[56:59], v[156:159], v[202:205], v[56:59]
	v_mfma_f32_16x16x32_bf16 v[44:47], v[128:131], v[210:213], v[44:47]
	v_mfma_f32_16x16x32_bf16 v[40:43], v[156:159], v[210:213], v[40:43]
	v_mfma_f32_16x16x32_bf16 v[28:31], v[128:131], v[232:235], v[28:31]
	v_mfma_f32_16x16x32_bf16 v[24:27], v[156:159], v[232:235], v[24:27]
	v_mfma_f32_16x16x32_bf16 v[12:15], v[128:131], v[240:243], v[12:15]
	v_mfma_f32_16x16x32_bf16 v[8:11], v[156:159], v[240:243], v[8:11]
	v_mfma_f32_16x16x32_bf16 v[60:63], v[132:135], v[206:209], v[60:63]
	v_mfma_f32_16x16x32_bf16 v[56:59], v[170:173], v[206:209], v[56:59]
	v_mfma_f32_16x16x32_bf16 v[44:47], v[132:135], v[228:231], v[44:47]
	v_mfma_f32_16x16x32_bf16 v[40:43], v[170:173], v[228:231], v[40:43]
	v_mfma_f32_16x16x32_bf16 v[28:31], v[132:135], v[236:239], v[28:31]
	v_mfma_f32_16x16x32_bf16 v[24:27], v[170:173], v[236:239], v[24:27]
	v_mfma_f32_16x16x32_bf16 v[12:15], v[132:135], v[244:247], v[12:15]
	v_mfma_f32_16x16x32_bf16 v[8:11], v[170:173], v[244:247], v[8:11]
	s_setprio 0
	s_setprio 1
	v_mfma_f32_16x16x32_bf16 v[52:55], v[174:177], v[202:205], v[52:55]
	v_mfma_f32_16x16x32_bf16 v[48:51], v[194:197], v[202:205], v[48:51]
	v_mfma_f32_16x16x32_bf16 v[36:39], v[174:177], v[210:213], v[36:39]
	v_mfma_f32_16x16x32_bf16 v[32:35], v[194:197], v[210:213], v[32:35]
	v_mfma_f32_16x16x32_bf16 v[20:23], v[174:177], v[232:235], v[20:23]
	v_mfma_f32_16x16x32_bf16 v[16:19], v[194:197], v[232:235], v[16:19]
	v_mfma_f32_16x16x32_bf16 v[4:7], v[174:177], v[240:243], v[4:7]
	v_mfma_f32_16x16x32_bf16 v[0:3], v[194:197], v[240:243], v[0:3]
	v_mfma_f32_16x16x32_bf16 v[52:55], v[178:181], v[206:209], v[52:55]
	v_mfma_f32_16x16x32_bf16 v[48:51], v[198:201], v[206:209], v[48:51]
	v_mfma_f32_16x16x32_bf16 v[36:39], v[178:181], v[228:231], v[36:39]
	v_mfma_f32_16x16x32_bf16 v[32:35], v[198:201], v[228:231], v[32:35]
	v_mfma_f32_16x16x32_bf16 v[20:23], v[178:181], v[236:239], v[20:23]
	v_mfma_f32_16x16x32_bf16 v[16:19], v[198:201], v[236:239], v[16:19]
	v_mfma_f32_16x16x32_bf16 v[4:7], v[178:181], v[244:247], v[4:7]
	v_mfma_f32_16x16x32_bf16 v[0:3], v[198:201], v[244:247], v[0:3]
	s_setprio 0
	s_barrier
	s_add_i32 s40, s40, 2
	s_add_u32 s0, s0, 0x100
	s_addc_u32 s1, s1, 0
	s_add_u32 s25, s25, 0x100
	s_addc_u32 s39, s39, 0
	s_cmp_gt_u32 s40, 13
	s_cbranch_scc0 .LBB0_509
	s_and_b64 vcc, exec, s[16:17]
	s_cbranch_vccz .LBB0_512
	s_barrier

; #define PG8_STAGE(bufoff, gbase, voff) do { _Pragma("unroll") for (int _i = 0; _i < 2; ++_i) \
;         __builtin_amdgcn_global_load_lds((const unsigned*)((const char*)(gbase) + (voff)[_i]), (PG8_LAS unsigned*)(lds + (bufoff) + ldsw + _i * 8192), 16, 0, 0); } while (0)
; #define PG8_LDA(dst, b, h) do { _Pragma("unroll") for (int m = 0; m < 4; ++m) _Pragma("unroll") for (int k = 0; k < 2; ++k) dst[m][k] = *(const PG8_LAS bf16x8*)(lds + PG8_SA(b, h) + aoff + m * 2048 + k * 1024); } while (0)
; #define PG8_LDB(dst, b, h) do { _Pragma("unroll") for (int n = 0; n < 2; ++n) _Pragma("unroll") for (int k = 0; k < 2; ++k) dst[n][k] = *(const PG8_LAS bf16x8*)(lds + PG8_SB(b, h) + boff + n * 2048 + k * 1024); } while (0)
; #define PG8_MMA(ai, bj, At, Bt) do { __builtin_amdgcn_s_setprio(1); _Pragma("unroll") for (int m = 0; m < 4; ++m) _Pragma("unroll") for (int n = 0; n < 2; ++n) _Pragma("unroll") for (int k = 0; k < 2; ++k) \
;         acc[ai][bj][m][n] = __builtin_amdgcn_mfma_f32_16x16x32_bf16(Bt[n][k], At[m][k], acc[ai][bj][m][n], 0, 0, 0); __builtin_amdgcn_s_setprio(0); } while (0)
; #define PG8_WAIT_V(n) asm volatile("s_waitcnt vmcnt(" #n ")" ::: "memory")
; #define PG8_WAIT_L(n) asm volatile("s_waitcnt lgkmcnt(" #n ")" ::: "memory")
; #define PG8_BAR __builtin_amdgcn_s_barrier()
; #define PG8_SCHED __builtin_amdgcn_sched_barrier(0)
; template <class Epi, class Sched, bool ALIGN_EPI = false, bool SP2 = false>
; __device__ __forceinline__ void gemm_phase(PG8_LAS unsigned char* lds, const Gemm g, const Sched& S, const Epi& E) {
;     ...
;             PG8_LDB(B0, 0, 0); PG8_LDB(B1, 0, 1); PG8_SCHED; PG8_LDA(At, 0, 0); PG8_STAGE(PG8_SA(1, 1), a1 + hstep, voffA);
;             PG8_WAIT_V(8); PG8_WAIT_L(0); PG8_BAR; PG8_MMA(0, 0, At, B0); PG8_MMA(0, 1, At, B1); PG8_BAR; PG8_SCHED;
;             PG8_LDA(At, 0, 1); PG8_STAGE(PG8_SB(0, 0), b2, voffB); PG8_STAGE(PG8_SB(0, 1), b2 + hstep, voffB); PG8_STAGE(PG8_SA(0, 0), a2, voffA);
;             PG8_WAIT_V(8); PG8_WAIT_L(0); PG8_BAR; PG8_MMA(1, 0, At, B0); PG8_MMA(1, 1, At, B1); PG8_BAR; PG8_SCHED;
.Lrs_in_a:
	s_add_i32 s54, 0, 0x14000
	v_add_u32_e32 v140, s39, v155
	v_add_u32_e32 v184, s54, v155
	ds_read_b128 v[128:131], v140
	ds_read_b128 v[132:135], v140 offset:1024
	ds_read_b128 v[136:139], v140 offset:2048
	ds_read_b128 v[140:143], v140 offset:3072
	ds_read_b128 v[170:173], v184
	ds_read_b128 v[174:177], v184 offset:1024
	ds_read_b128 v[180:183], v184 offset:2048
	ds_read_b128 v[194:197], v184 offset:3072
	v_lshl_add_u64 v[214:215], s[0:1], 0, v[166:167]
	s_add_i32 m0, s23, 0xc000
	ds_read_b128 v[198:201], v179
	ds_read_b128 v[202:205], v179 offset:1024
	ds_read_b128 v[206:209], v179 offset:2048
	ds_read_b128 v[210:213], v179 offset:3072
	ds_read_b128 v[228:231], v179 offset:4096
	ds_read_b128 v[232:235], v179 offset:5120
	ds_read_b128 v[236:239], v179 offset:6144
	ds_read_b128 v[240:243], v179 offset:7168
	global_load_lds_dwordx4 v[214:215], off
	v_lshl_add_u64 v[214:215], s[0:1], 0, v[168:169]
	s_add_i32 m0, s23, 0xe000
	s_nop 0
	global_load_lds_dwordx4 v[214:215], off
	s_nop 0
	s_waitcnt vmcnt(8)
	s_waitcnt lgkmcnt(0)
	s_barrier
	s_setprio 1
	s_waitcnt lgkmcnt(0)
	v_mfma_f32_16x16x32_bf16 v[124:127], v[128:131], v[198:201], v[124:127]
	v_mfma_f32_16x16x32_bf16 v[120:123], v[136:139], v[198:201], v[120:123]
	v_mfma_f32_16x16x32_bf16 v[108:111], v[128:131], v[206:209], v[108:111]
	v_mfma_f32_16x16x32_bf16 v[104:107], v[136:139], v[206:209], v[104:107]
	v_mfma_f32_16x16x32_bf16 v[92:95], v[128:131], v[228:231], v[92:95]
	v_mfma_f32_16x16x32_bf16 v[88:91], v[136:139], v[228:231], v[88:91]
	v_mfma_f32_16x16x32_bf16 v[76:79], v[128:131], v[236:239], v[76:79]
	v_mfma_f32_16x16x32_bf16 v[72:75], v[136:139], v[236:239], v[72:75]
	v_mfma_f32_16x16x32_bf16 v[124:127], v[132:135], v[202:205], v[124:127]
	v_mfma_f32_16x16x32_bf16 v[120:123], v[140:143], v[202:205], v[120:123]
	v_mfma_f32_16x16x32_bf16 v[108:111], v[132:135], v[210:213], v[108:111]
	v_mfma_f32_16x16x32_bf16 v[104:107], v[140:143], v[210:213], v[104:107]
	v_mfma_f32_16x16x32_bf16 v[92:95], v[132:135], v[232:235], v[92:95]
	v_mfma_f32_16x16x32_bf16 v[88:91], v[140:143], v[232:235], v[88:91]
	v_mfma_f32_16x16x32_bf16 v[76:79], v[132:135], v[240:243], v[76:79]
	v_mfma_f32_16x16x32_bf16 v[72:75], v[140:143], v[240:243], v[72:75]
	s_setprio 0
	s_setprio 1
	v_mfma_f32_16x16x32_bf16 v[116:119], v[170:173], v[198:201], v[116:119]
	v_mfma_f32_16x16x32_bf16 v[112:115], v[180:183], v[198:201], v[112:115]
	v_mfma_f32_16x16x32_bf16 v[100:103], v[170:173], v[206:209], v[100:103]
	v_mfma_f32_16x16x32_bf16 v[96:99], v[180:183], v[206:209], v[96:99]
	v_mfma_f32_16x16x32_bf16 v[84:87], v[170:173], v[228:231], v[84:87]
	v_mfma_f32_16x16x32_bf16 v[80:83], v[180:183], v[228:231], v[80:83]
	v_mfma_f32_16x16x32_bf16 v[68:71], v[170:173], v[236:239], v[68:71]
	v_mfma_f32_16x16x32_bf16 v[64:67], v[180:183], v[236:239], v[64:67]
	v_mfma_f32_16x16x32_bf16 v[116:119], v[174:177], v[202:205], v[116:119]
	v_mfma_f32_16x16x32_bf16 v[112:115], v[194:197], v[202:205], v[112:115]
	v_mfma_f32_16x16x32_bf16 v[100:103], v[174:177], v[210:213], v[100:103]
	v_mfma_f32_16x16x32_bf16 v[96:99], v[194:197], v[210:213], v[96:99]
	v_mfma_f32_16x16x32_bf16 v[84:87], v[174:177], v[232:235], v[84:87]
	v_mfma_f32_16x16x32_bf16 v[80:83], v[194:197], v[232:235], v[80:83]
	v_mfma_f32_16x16x32_bf16 v[68:71], v[174:177], v[240:243], v[68:71]
	v_mfma_f32_16x16x32_bf16 v[64:67], v[194:197], v[240:243], v[64:67]
	s_setprio 0
	s_barrier
	s_add_i32 s39, s39, s22
	v_lshl_add_u64 v[214:215], s[2:3], 0, v[148:149]
	s_mov_b32 m0, s39
	ds_read_b128 v[198:201], v179 offset:16384
	ds_read_b128 v[202:205], v179 offset:17408
	ds_read_b128 v[206:209], v179 offset:18432
	ds_read_b128 v[210:213], v179 offset:19456
	ds_read_b128 v[228:231], v179 offset:20480
	ds_read_b128 v[232:235], v179 offset:21504
	ds_read_b128 v[236:239], v179 offset:22528
	ds_read_b128 v[240:243], v179 offset:23552
	global_load_lds_dwordx4 v[214:215], off
	s_add_i32 m0, s39, 0x2000
	s_add_u32 s40, s2, 0x40000
	v_lshl_add_u64 v[224:225], s[2:3], 0, v[144:145]
	s_addc_u32 s41, s3, 0
	s_add_i32 s39, s54, s22
	global_load_lds_dwordx4 v[224:225], off
	v_lshl_add_u64 v[244:245], s[40:41], 0, v[148:149]
	s_mov_b32 m0, s39
	v_lshl_add_u64 v[246:247], s[24:25], 0, v[146:147]
	global_load_lds_dwordx4 v[244:245], off
	v_lshl_add_u64 v[244:245], s[40:41], 0, v[144:145]
	s_add_i32 m0, s39, 0x2000
	s_nop 0
	global_load_lds_dwordx4 v[244:245], off
	v_lshl_add_u64 v[244:245], s[24:25], 0, v[150:151]
	s_mov_b32 m0, s23
	s_nop 0
	global_load_lds_dwordx4 v[244:245], off
	s_mov_b32 m0, s44
	s_nop 0
	global_load_lds_dwordx4 v[246:247], off
	s_nop 0
	s_waitcnt vmcnt(8)
	s_waitcnt lgkmcnt(0)
	s_barrier
; __device__ __forceinline__ float sum4(const f32x4 a) { return (a[0] + a[1]) + (a[2] + a[3]); }
; #define PG8_STAGE(bufoff, gbase, voff) do { _Pragma("unroll") for (int _i = 0; _i < 2; ++_i) \
;         __builtin_amdgcn_global_load_lds((const unsigned*)((const char*)(gbase) + (voff)[_i]), (PG8_LAS unsigned*)(lds + (bufoff) + ldsw + _i * 8192), 16, 0, 0); } while (0)
; #define PG8_LDA(dst, b, h) do { _Pragma("unroll") for (int m = 0; m < 4; ++m) _Pragma("unroll") for (int k = 0; k < 2; ++k) dst[m][k] = *(const PG8_LAS bf16x8*)(lds + PG8_SA(b, h) + aoff + m * 2048 + k * 1024); } while (0)
; #define PG8_LDB(dst, b, h) do { _Pragma("unroll") for (int n = 0; n < 2; ++n) _Pragma("unroll") for (int k = 0; k < 2; ++k) dst[n][k] = *(const PG8_LAS bf16x8*)(lds + PG8_SB(b, h) + boff + n * 2048 + k * 1024); } while (0)
; #define PG8_MMA(ai, bj, At, Bt) do { __builtin_amdgcn_s_setprio(1); _Pragma("unroll") for (int m = 0; m < 4; ++m) _Pragma("unroll") for (int n = 0; n < 2; ++n) _Pragma("unroll") for (int k = 0; k < 2; ++k) \
;         acc[ai][bj][m][n] = __builtin_amdgcn_mfma_f32_16x16x32_bf16(Bt[n][k], At[m][k], acc[ai][bj][m][n], 0, 0, 0); __builtin_amdgcn_s_setprio(0); } while (0)
; #define PG8_WAIT_V(n) asm volatile("s_waitcnt vmcnt(" #n ")" ::: "memory")
; #define PG8_WAIT_L(n) asm volatile("s_waitcnt lgkmcnt(" #n ")" ::: "memory")
; #define PG8_BAR __builtin_amdgcn_s_barrier()
; #define PG8_SCHED __builtin_amdgcn_sched_barrier(0)
; __device__ __forceinline__ float row_rstd(const float* ps_row) {
;     const f32x4* p = (const f32x4*)ps_row; const f32x4 a = p[0], b = p[1], c = p[2], d = p[3];
;     const float s = (sum4(a) + sum4(b)) + (sum4(c) + sum4(d));
;     return 1.0f / sqrtf(s * (1.0f / 1024.0f) + E_EPS);
; template <class Epi, class Sched, bool ALIGN_EPI = false, bool SP2 = false>
; __device__ __forceinline__ void gemm_phase(PG8_LAS unsigned char* lds, const Gemm g, const Sched& S, const Epi& E) {
;     ...
;             PG8_WAIT_V(8); PG8_WAIT_L(0); PG8_BAR; PG8_MMA(1, 0, At, B0); PG8_MMA(1, 1, At, B1); PG8_BAR; PG8_SCHED;
;             PG8_LDB(B0, 1, 0); PG8_LDB(B1, 1, 1); PG8_SCHED; PG8_LDA(At, 1, 0); PG8_STAGE(PG8_SA(0, 1), a2 + hstep, voffA);
;             PG8_WAIT_V(8); PG8_WAIT_L(0); PG8_BAR; PG8_MMA(0, 0, At, B0); PG8_MMA(0, 1, At, B1); PG8_BAR; PG8_SCHED;
	s_setprio 1
	s_waitcnt lgkmcnt(0)
	v_mfma_f32_16x16x32_bf16 v[60:63], v[128:131], v[198:201], v[60:63]
	v_mfma_f32_16x16x32_bf16 v[56:59], v[136:139], v[198:201], v[56:59]
	v_mfma_f32_16x16x32_bf16 v[44:47], v[128:131], v[206:209], v[44:47]
	v_mfma_f32_16x16x32_bf16 v[40:43], v[136:139], v[206:209], v[40:43]
	v_mfma_f32_16x16x32_bf16 v[28:31], v[128:131], v[228:231], v[28:31]
	v_mfma_f32_16x16x32_bf16 v[24:27], v[136:139], v[228:231], v[24:27]
	v_mfma_f32_16x16x32_bf16 v[12:15], v[128:131], v[236:239], v[12:15]
	v_mfma_f32_16x16x32_bf16 v[8:11], v[136:139], v[236:239], v[8:11]
	v_mfma_f32_16x16x32_bf16 v[60:63], v[132:135], v[202:205], v[60:63]
	v_mfma_f32_16x16x32_bf16 v[56:59], v[140:143], v[202:205], v[56:59]
	v_mfma_f32_16x16x32_bf16 v[44:47], v[132:135], v[210:213], v[44:47]
	v_mfma_f32_16x16x32_bf16 v[40:43], v[140:143], v[210:213], v[40:43]
	v_mfma_f32_16x16x32_bf16 v[28:31], v[132:135], v[232:235], v[28:31]
	v_mfma_f32_16x16x32_bf16 v[24:27], v[140:143], v[232:235], v[24:27]
	v_mfma_f32_16x16x32_bf16 v[12:15], v[132:135], v[240:243], v[12:15]
	v_mfma_f32_16x16x32_bf16 v[8:11], v[140:143], v[240:243], v[8:11]
	s_setprio 0
	s_setprio 1
	v_mfma_f32_16x16x32_bf16 v[52:55], v[170:173], v[198:201], v[52:55]
	v_mfma_f32_16x16x32_bf16 v[48:51], v[180:183], v[198:201], v[48:51]
	v_mfma_f32_16x16x32_bf16 v[36:39], v[170:173], v[206:209], v[36:39]
	v_mfma_f32_16x16x32_bf16 v[32:35], v[180:183], v[206:209], v[32:35]
	v_mfma_f32_16x16x32_bf16 v[20:23], v[170:173], v[228:231], v[20:23]
	v_mfma_f32_16x16x32_bf16 v[16:19], v[180:183], v[228:231], v[16:19]
	v_mfma_f32_16x16x32_bf16 v[4:7], v[170:173], v[236:239], v[4:7]
	v_mfma_f32_16x16x32_bf16 v[0:3], v[180:183], v[236:239], v[0:3]
	v_mfma_f32_16x16x32_bf16 v[52:55], v[174:177], v[202:205], v[52:55]
	v_mfma_f32_16x16x32_bf16 v[48:51], v[194:197], v[202:205], v[48:51]
	v_mfma_f32_16x16x32_bf16 v[36:39], v[174:177], v[210:213], v[36:39]
	v_mfma_f32_16x16x32_bf16 v[32:35], v[194:197], v[210:213], v[32:35]
	v_mfma_f32_16x16x32_bf16 v[20:23], v[174:177], v[232:235], v[20:23]
	v_mfma_f32_16x16x32_bf16 v[16:19], v[194:197], v[232:235], v[16:19]
	v_mfma_f32_16x16x32_bf16 v[4:7], v[174:177], v[240:243], v[4:7]
	v_mfma_f32_16x16x32_bf16 v[0:3], v[194:197], v[240:243], v[0:3]
	s_setprio 0
	s_barrier
	s_add_i32 s39, 0, 0x18000
	s_add_i32 s40, 0, 0x1c000
	s_cmp_eq_u32 s38, 12
	s_cbranch_scc0 .Lrs_in_b
	v_add_f32_e32 v190, v190, v191
	v_add_f32_e32 v226, v226, v227
	v_add_f32_e32 v217, v217, v220
	v_add_f32_e32 v223, v223, v250
	v_add_f32_e32 v190, v190, v226
	v_add_f32_e32 v217, v217, v223
	v_add_f32_e32 v190, v190, v217
	s_nop 1
	v_add_f32_dpp v190, v190, v190 quad_perm:[1,0,3,2] row_mask:0xf bank_mask:0xf
	s_mov_b32 s98, 0xf800000
	v_fmamk_f32 v190, v190, 0x3a800000, v218
	v_mul_f32_e32 v191, 0x4f800000, v190
	v_cmp_gt_f32_e32 vcc, s98, v190
	s_nop 1
	v_cndmask_b32_e32 v190, v190, v191, vcc
	v_sqrt_f32_e32 v191, v190
	s_nop 0
	v_add_u32_e32 v217, -1, v191
	v_add_u32_e32 v220, 1, v191
	v_fma_f32 v223, -v217, v191, v190
	v_fma_f32 v226, -v220, v191, v190
	v_cmp_ge_f32_e64 s[98:99], 0, v223
	s_nop 1
	v_cndmask_b32_e64 v191, v191, v217, s[98:99]
	v_cmp_lt_f32_e64 s[98:99], 0, v226
	s_nop 1
	v_cndmask_b32_e64 v191, v191, v220, s[98:99]
	v_mul_f32_e32 v217, 0x37800000, v191
	v_cndmask_b32_e32 v191, v191, v217, vcc
	v_cmp_class_f32_e32 vcc, v190, v219
	s_nop 1
	v_cndmask_b32_e32 v190, v191, v190, vcc
	v_div_scale_f32 v191, s[98:99], v190, v190, 1.0
	v_rcp_f32_e32 v217, v191
	v_div_scale_f32 v220, vcc, 1.0, v190, 1.0
	v_fma_f32 v223, -v191, v217, 1.0
	v_fmac_f32_e32 v217, v223, v217
	v_mul_f32_e32 v223, v220, v217
	v_fma_f32 v226, -v191, v223, v220
	v_fmac_f32_e32 v223, v226, v217
	v_fma_f32 v191, -v191, v223, v220
	v_div_fmas_f32 v191, v191, v217, v223
	v_div_fixup_f32 v190, v191, v190, 1.0
	v_lshrrev_b32_e32 v250, 1, v216
	v_lshl_add_u32 v250, v250, 2, 0
	v_add_u32_e32 v250, 0x20000, v250
	ds_write_b32 v250, v190
.Lrs_in_b:
	v_add_u32_e32 v140, s39, v155
	v_add_u32_e32 v184, s40, v155
	ds_read_b128 v[128:131], v140
	ds_read_b128 v[132:135], v140 offset:1024
	ds_read_b128 v[136:139], v140 offset:2048
	ds_read_b128 v[140:143], v140 offset:3072
	ds_read_b128 v[170:173], v184
	ds_read_b128 v[174:177], v184 offset:1024
	ds_read_b128 v[180:183], v184 offset:2048
	ds_read_b128 v[194:197], v184 offset:3072
	s_add_u32 s24, s24, 0x40000
	s_addc_u32 s25, s25, 0
	s_mov_b32 m0, s45
	v_lshl_add_u64 v[248:249], s[24:25], 0, v[150:151]
	ds_read_b128 v[198:201], v179 offset:32768
	ds_read_b128 v[202:205], v179 offset:33792
	ds_read_b128 v[206:209], v179 offset:34816
	ds_read_b128 v[210:213], v179 offset:35840
	ds_read_b128 v[228:231], v179 offset:36864
	ds_read_b128 v[232:235], v179 offset:37888
	ds_read_b128 v[236:239], v179 offset:38912
	ds_read_b128 v[240:243], v179 offset:39936
	global_load_lds_dwordx4 v[248:249], off
	v_lshl_add_u64 v[248:249], s[24:25], 0, v[146:147]
	s_mov_b32 m0, s46
	s_nop 0
	global_load_lds_dwordx4 v[248:249], off
	s_nop 0
	s_waitcnt vmcnt(8)
	s_waitcnt lgkmcnt(0)
	s_barrier
; #define PG8_STAGE(bufoff, gbase, voff) do { _Pragma("unroll") for (int _i = 0; _i < 2; ++_i) \
;         __builtin_amdgcn_global_load_lds((const unsigned*)((const char*)(gbase) + (voff)[_i]), (PG8_LAS unsigned*)(lds + (bufoff) + ldsw + _i * 8192), 16, 0, 0); } while (0)
; #define PG8_LDA(dst, b, h) do { _Pragma("unroll") for (int m = 0; m < 4; ++m) _Pragma("unroll") for (int k = 0; k < 2; ++k) dst[m][k] = *(const PG8_LAS bf16x8*)(lds + PG8_SA(b, h) + aoff + m * 2048 + k * 1024); } while (0)
; #define PG8_MMA(ai, bj, At, Bt) do { __builtin_amdgcn_s_setprio(1); _Pragma("unroll") for (int m = 0; m < 4; ++m) _Pragma("unroll") for (int n = 0; n < 2; ++n) _Pragma("unroll") for (int k = 0; k < 2; ++k) \
;         acc[ai][bj][m][n] = __builtin_amdgcn_mfma_f32_16x16x32_bf16(Bt[n][k], At[m][k], acc[ai][bj][m][n], 0, 0, 0); __builtin_amdgcn_s_setprio(0); } while (0)
; #define PG8_WAIT_V(n) asm volatile("s_waitcnt vmcnt(" #n ")" ::: "memory")
; #define PG8_WAIT_L(n) asm volatile("s_waitcnt lgkmcnt(" #n ")" ::: "memory")
; #define PG8_BAR __builtin_amdgcn_s_barrier()
; #define PG8_SCHED __builtin_amdgcn_sched_barrier(0)
; template <class Epi, class Sched, bool ALIGN_EPI = false, bool SP2 = false>
; __device__ __forceinline__ void gemm_phase(PG8_LAS unsigned char* lds, const Gemm g, const Sched& S, const Epi& E) {
;     ...
;             PG8_WAIT_V(8); PG8_WAIT_L(0); PG8_BAR; PG8_MMA(0, 0, At, B0); PG8_MMA(0, 1, At, B1); PG8_BAR; PG8_SCHED;
;             PG8_LDA(At, 1, 1); PG8_STAGE(PG8_SB(1, 0), b3, voffB); PG8_STAGE(PG8_SB(1, 1), b3 + hstep, voffB); PG8_STAGE(PG8_SA(1, 0), a3, voffA);
;             PG8_WAIT_V(8); PG8_WAIT_L(0); PG8_BAR; PG8_MMA(1, 0, At, B0); PG8_MMA(1, 1, At, B1); PG8_BAR; PG8_SCHED;
	s_setprio 1
	s_waitcnt lgkmcnt(0)
	v_mfma_f32_16x16x32_bf16 v[124:127], v[128:131], v[198:201], v[124:127]
	v_mfma_f32_16x16x32_bf16 v[120:123], v[136:139], v[198:201], v[120:123]
	v_mfma_f32_16x16x32_bf16 v[108:111], v[128:131], v[206:209], v[108:111]
	v_mfma_f32_16x16x32_bf16 v[104:107], v[136:139], v[206:209], v[104:107]
	v_mfma_f32_16x16x32_bf16 v[92:95], v[128:131], v[228:231], v[92:95]
	v_mfma_f32_16x16x32_bf16 v[88:91], v[136:139], v[228:231], v[88:91]
	v_mfma_f32_16x16x32_bf16 v[76:79], v[128:131], v[236:239], v[76:79]
	v_mfma_f32_16x16x32_bf16 v[72:75], v[136:139], v[236:239], v[72:75]
	v_mfma_f32_16x16x32_bf16 v[124:127], v[132:135], v[202:205], v[124:127]
	v_mfma_f32_16x16x32_bf16 v[120:123], v[140:143], v[202:205], v[120:123]
	v_mfma_f32_16x16x32_bf16 v[108:111], v[132:135], v[210:213], v[108:111]
	v_mfma_f32_16x16x32_bf16 v[104:107], v[140:143], v[210:213], v[104:107]
	v_mfma_f32_16x16x32_bf16 v[92:95], v[132:135], v[232:235], v[92:95]
	v_mfma_f32_16x16x32_bf16 v[88:91], v[140:143], v[232:235], v[88:91]
	v_mfma_f32_16x16x32_bf16 v[76:79], v[132:135], v[240:243], v[76:79]
	v_mfma_f32_16x16x32_bf16 v[72:75], v[140:143], v[240:243], v[72:75]
	s_setprio 0
	s_setprio 1
	v_mfma_f32_16x16x32_bf16 v[116:119], v[170:173], v[198:201], v[116:119]
	v_mfma_f32_16x16x32_bf16 v[112:115], v[180:183], v[198:201], v[112:115]
	v_mfma_f32_16x16x32_bf16 v[100:103], v[170:173], v[206:209], v[100:103]
	v_mfma_f32_16x16x32_bf16 v[96:99], v[180:183], v[206:209], v[96:99]
	v_mfma_f32_16x16x32_bf16 v[84:87], v[170:173], v[228:231], v[84:87]
	v_mfma_f32_16x16x32_bf16 v[80:83], v[180:183], v[228:231], v[80:83]
	v_mfma_f32_16x16x32_bf16 v[68:71], v[170:173], v[236:239], v[68:71]
	v_mfma_f32_16x16x32_bf16 v[64:67], v[180:183], v[236:239], v[64:67]
	v_mfma_f32_16x16x32_bf16 v[116:119], v[174:177], v[202:205], v[116:119]
	v_mfma_f32_16x16x32_bf16 v[112:115], v[194:197], v[202:205], v[112:115]
	v_mfma_f32_16x16x32_bf16 v[100:103], v[174:177], v[210:213], v[100:103]
	v_mfma_f32_16x16x32_bf16 v[96:99], v[194:197], v[210:213], v[96:99]
	v_mfma_f32_16x16x32_bf16 v[84:87], v[174:177], v[232:235], v[84:87]
	v_mfma_f32_16x16x32_bf16 v[80:83], v[194:197], v[232:235], v[80:83]
	v_mfma_f32_16x16x32_bf16 v[68:71], v[174:177], v[240:243], v[68:71]
	v_mfma_f32_16x16x32_bf16 v[64:67], v[194:197], v[240:243], v[64:67]
	s_setprio 0
	s_barrier
	s_add_i32 s24, s39, s22
	v_lshl_add_u64 v[214:215], v[214:215], 0, s[96:97]
	s_mov_b32 m0, s24
	ds_read_b128 v[198:201], v179 offset:49152
	ds_read_b128 v[202:205], v179 offset:50176
	ds_read_b128 v[206:209], v179 offset:51200
	ds_read_b128 v[210:213], v179 offset:52224
	ds_read_b128 v[228:231], v179 offset:53248
	ds_read_b128 v[232:235], v179 offset:54272
	ds_read_b128 v[236:239], v179 offset:55296
	ds_read_b128 v[240:243], v179 offset:56320
	global_load_lds_dwordx4 v[214:215], off
	s_add_i32 m0, s24, 0x2000
	s_add_u32 s2, s2, 0x40080
	v_lshl_add_u64 v[214:215], v[224:225], 0, s[96:97]
	s_addc_u32 s3, s3, 0
	s_add_i32 s24, s40, s22
	global_load_lds_dwordx4 v[214:215], off
	v_lshl_add_u64 v[214:215], s[2:3], 0, v[148:149]
	s_mov_b32 m0, s24
	s_nop 0
	global_load_lds_dwordx4 v[214:215], off
	v_lshl_add_u64 v[214:215], s[2:3], 0, v[144:145]
	s_add_i32 m0, s24, 0x2000
	s_nop 0
	global_load_lds_dwordx4 v[214:215], off
	v_lshl_add_u64 v[214:215], v[244:245], 0, s[96:97]
	s_mov_b32 m0, s47
	s_nop 0
	global_load_lds_dwordx4 v[214:215], off
	v_lshl_add_u64 v[214:215], v[246:247], 0, s[96:97]
	s_mov_b32 m0, s48
	s_nop 0
	global_load_lds_dwordx4 v[214:215], off
	s_waitcnt vmcnt(8)
	s_waitcnt lgkmcnt(0)
	s_barrier
	s_setprio 1
	s_waitcnt lgkmcnt(0)
	v_mfma_f32_16x16x32_bf16 v[60:63], v[128:131], v[198:201], v[60:63]
	v_mfma_f32_16x16x32_bf16 v[56:59], v[136:139], v[198:201], v[56:59]
	v_mfma_f32_16x16x32_bf16 v[44:47], v[128:131], v[206:209], v[44:47]
	v_mfma_f32_16x16x32_bf16 v[40:43], v[136:139], v[206:209], v[40:43]
	v_mfma_f32_16x16x32_bf16 v[28:31], v[128:131], v[228:231], v[28:31]
	v_mfma_f32_16x16x32_bf16 v[24:27], v[136:139], v[228:231], v[24:27]
	v_mfma_f32_16x16x32_bf16 v[12:15], v[128:131], v[236:239], v[12:15]
	v_mfma_f32_16x16x32_bf16 v[8:11], v[136:139], v[236:239], v[8:11]
	v_mfma_f32_16x16x32_bf16 v[60:63], v[132:135], v[202:205], v[60:63]
	v_mfma_f32_16x16x32_bf16 v[56:59], v[140:143], v[202:205], v[56:59]
	v_mfma_f32_16x16x32_bf16 v[44:47], v[132:135], v[210:213], v[44:47]
	v_mfma_f32_16x16x32_bf16 v[40:43], v[140:143], v[210:213], v[40:43]
	v_mfma_f32_16x16x32_bf16 v[28:31], v[132:135], v[232:235], v[28:31]
	v_mfma_f32_16x16x32_bf16 v[24:27], v[140:143], v[232:235], v[24:27]
	v_mfma_f32_16x16x32_bf16 v[12:15], v[132:135], v[240:243], v[12:15]
	v_mfma_f32_16x16x32_bf16 v[8:11], v[140:143], v[240:243], v[8:11]
	s_setprio 0
	s_setprio 1
	v_mfma_f32_16x16x32_bf16 v[52:55], v[170:173], v[198:201], v[52:55]
	v_mfma_f32_16x16x32_bf16 v[48:51], v[180:183], v[198:201], v[48:51]
	v_mfma_f32_16x16x32_bf16 v[36:39], v[170:173], v[206:209], v[36:39]
	v_mfma_f32_16x16x32_bf16 v[32:35], v[180:183], v[206:209], v[32:35]
	v_mfma_f32_16x16x32_bf16 v[20:23], v[170:173], v[228:231], v[20:23]
	v_mfma_f32_16x16x32_bf16 v[16:19], v[180:183], v[228:231], v[16:19]
	v_mfma_f32_16x16x32_bf16 v[4:7], v[170:173], v[236:239], v[4:7]
	v_mfma_f32_16x16x32_bf16 v[0:3], v[180:183], v[236:239], v[0:3]
	v_mfma_f32_16x16x32_bf16 v[52:55], v[174:177], v[202:205], v[52:55]
	v_mfma_f32_16x16x32_bf16 v[48:51], v[194:197], v[202:205], v[48:51]
	v_mfma_f32_16x16x32_bf16 v[36:39], v[174:177], v[210:213], v[36:39]
	v_mfma_f32_16x16x32_bf16 v[32:35], v[194:197], v[210:213], v[32:35]
	v_mfma_f32_16x16x32_bf16 v[20:23], v[174:177], v[232:235], v[20:23]
	v_mfma_f32_16x16x32_bf16 v[16:19], v[194:197], v[232:235], v[16:19]
	v_mfma_f32_16x16x32_bf16 v[4:7], v[174:177], v[240:243], v[4:7]
	v_mfma_f32_16x16x32_bf16 v[0:3], v[194:197], v[240:243], v[0:3]
	s_setprio 0
	s_barrier
	s_add_i32 s38, s38, 2
	s_add_u32 s0, s0, 0x100
	s_addc_u32 s1, s1, 0
	s_add_u32 s11, s11, 0x100
	s_addc_u32 s19, s19, 0
	s_cmp_gt_u32 s38, 13
	s_cbranch_scc0 .LBB0_533
	s_and_b64 vcc, exec, s[14:15]
	s_cbranch_vccz .LBB0_536
	s_barrier
